# RWKV chain: copy-propagated K=16 MFMA operands (U2) and y-row store addresses as first+k*stride with SALU multiply + v_lshl_add_u64 (V2)
# baseline (speedup 1.0000x reference)
.LBB0_362:
	s_or_b64 exec, exec, s[28:29]
	s_waitcnt lgkmcnt(0)
	s_barrier
	ds_read_b128 v[40:43], v214 offset:9216
	ds_read_b128 v[48:51], v214 offset:18496
	ds_read_b128 v[56:59], v214 offset:9280
	ds_read_b128 v[60:63], v214 offset:23040
	ds_read_b128 v[36:39], v214 offset:18432
	s_nop 0
	s_nop 0
	s_nop 0
	ds_read_b128 v[64:67], v214 offset:13824
	s_waitcnt lgkmcnt(1)
	v_mfma_f32_16x16x32_f16 v[52:55], v[40:43], v[36:39], 0
	s_nop 0
	s_nop 0
	s_nop 0
	ds_read_b128 v[68:71], v214 offset:13888
	ds_read_b128 v[72:75], v214 offset:23104
	v_add_u32_e32 v80, 0x1000, v220
	s_nop 0
	v_mfma_f32_16x16x32_f16 v[52:55], v[56:59], v[48:51], v[52:55]
	s_nop 0
	s_nop 0
	s_nop 0
	v_mfma_f32_16x16x32_f16 v[44:47], v[36:39], v[40:43], 0
	s_nop 3
	v_cvt_f16_f32_e32 v0, v52
	v_cvt_f16_f32_e32 v1, v54
	v_cvt_f16_f32_e32 v2, v55
	v_mfma_f32_16x16x32_f16 v[44:47], v[48:51], v[56:59], v[44:47]
	v_cndmask_b32_e64 v79, 0, v0, s[12:13]
	v_cvt_f16_f32_e32 v0, v53
	v_cndmask_b32_e64 v54, 0, v1, s[18:19]
	s_nop 0
	v_mfma_f32_16x16x32_f16 v[40:43], v[60:63], v[40:43], 0
	v_cndmask_b32_e64 v55, 0, v2, s[22:23]
	s_nop 1
	v_cndmask_b32_e64 v76, 0, v44, s[10:11]
	v_cndmask_b32_e64 v77, 0, v45, s[14:15]
	s_nop 0
	s_waitcnt lgkmcnt(2)
	v_mfma_f32_16x16x32_f16 v[36:39], v[36:39], v[64:67], 0
	v_cndmask_b32_e64 v52, 0, v46, s[16:17]
	v_cndmask_b32_e64 v78, 0, v47, s[20:21]
	v_cndmask_b32_e64 v53, v0, 0, s[10:11]
	v_mfma_f32_16x16x32_f16 v[44:47], v[60:63], v[64:67], 0
	v_cvt_pk_f16_f32 v1, v52, v78
	v_cvt_pk_f16_f32 v0, v76, v77
	s_nop 0
	s_nop 0
	s_waitcnt lgkmcnt(0)
	v_mfma_f32_16x16x32_f16 v[60:63], v[72:75], v[56:59], v[40:43]
	v_add_f32_e32 v56, v215, v76
	v_add_f32_e32 v57, v217, v77
	v_add_f32_e32 v58, v218, v52
	v_mfma_f32_16x16x32_f16 v[40:43], v[48:51], v[68:71], v[36:39]
	v_add_f32_e32 v59, v219, v78
	v_cvt_pk_f16_f32 v67, v26, v27
	v_cvt_pk_f16_f32 v66, v24, v25
	v_pack_b32_f16 v37, v54, v55
	v_pack_b32_f16 v36, v79, v53
	s_nop 0
	s_nop 0
	v_mfma_f32_16x16x32_f16 v[52:55], v[72:75], v[68:71], v[44:47]
	ds_read2_b64 v[68:71], v220 offset0:8 offset1:12
	v_cvt_pk_f16_f32 v65, v30, v31
	v_cvt_pk_f16_f32 v64, v28, v29
	v_mfma_f32_16x16x16_f16 v[48:51], v[0:1], v[36:37], 0
	v_cvt_pk_f16_f32 v45, v58, v59
	v_cvt_pk_f16_f32 v44, v56, v57
	s_nop 0
	v_mfma_f32_16x16x16_f16 v[36:39], v[36:37], v[0:1], 0
	s_nop 0
	s_nop 2
	v_cvt_pk_f16_f32 v1, v50, v51
	v_cvt_pk_f16_f32 v0, v48, v49
	s_nop 0
	s_nop 0
	v_cvt_pk_f16_f32 v49, v38, v39
	v_cvt_pk_f16_f32 v48, v36, v37
	v_mfma_f32_16x16x16_f16 v[44:47], v[0:1], v[44:45], v[56:59]
	s_nop 0
	s_nop 0
	s_nop 0
	v_mfma_f32_16x16x16_f16 v[36:39], v[48:49], v[0:1], 0
	ds_read2_b64 v[128:131], v220 offset1:4
	v_cvt_pk_f16_f32 v59, v34, v35
	v_cvt_pk_f16_f32 v58, v32, v33
	v_cvt_pk_f16_f32 v57, v22, v23
	v_mfma_f32_16x16x16_f16 v[48:51], v[0:1], v[48:49], 0
	v_cvt_pk_f16_f32 v56, v20, v21
	s_nop 2
	v_cvt_pk_f16_f32 v1, v38, v39
	v_cvt_pk_f16_f32 v0, v36, v37
	v_cvt_pk_f16_f32 v37, v46, v47
	v_cvt_pk_f16_f32 v36, v44, v45
	s_nop 0
	s_nop 0
	v_cvt_f16_f32_e32 v52, v52
	s_add_i32 s27, s26, 1
	v_mfma_f32_16x16x16_f16 v[44:47], v[0:1], v[36:37], v[44:47]
	v_cvt_pk_f16_f32 v37, v50, v51
	v_cvt_pk_f16_f32 v36, v48, v49
	s_nop 0
	s_nop 0
	v_mfma_f32_16x16x16_f16 v[36:39], v[36:37], v[0:1], 0
	s_nop 2
	v_cvt_pk_f16_f32 v1, v46, v47
	v_cvt_pk_f16_f32 v0, v44, v45
	s_nop 2
	v_cvt_pk_f16_f32 v49, v38, v39
	v_cvt_pk_f16_f32 v48, v36, v37
	s_nop 0
	s_nop 0
	s_waitcnt lgkmcnt(0)
	v_mfma_f32_16x16x32_f16 v[36:39], v[128:131], v[56:59], 0
	v_mfma_f32_16x16x16_f16 v[44:47], v[48:49], v[0:1], v[44:47]
	v_cvt_f16_f32_e32 v0, v60
	v_cvt_f16_f32_e32 v1, v61
	v_cvt_f16_f32_e32 v2, v62
	v_cvt_f16_f32_e32 v48, v63
	v_mfma_f32_16x16x32_f16 v[76:79], v[68:71], v[64:67], v[36:39]
	ds_read2_b64 v[72:75], v80 offset0:64 offset1:68
	ds_read2st64_b64 v[132:135], v221 offset0:20 offset1:25
	ds_read2_b64 v[68:71], v80 offset0:72 offset1:76
	s_nop 0
	s_nop 0
	v_cndmask_b32_e64 v0, 0, v0, s[10:11]
	v_cndmask_b32_e64 v49, 0, v1, s[14:15]
	v_cndmask_b32_e64 v1, 0, v2, s[16:17]
	v_cndmask_b32_e64 v2, 0, v48, s[20:21]
	v_pack_b32_f16 v1, v1, v2
	v_pack_b32_f16 v0, v0, v49
	s_nop 0
	s_nop 0
	s_waitcnt lgkmcnt(1)
	s_nop 0
	s_nop 0
	ds_read2_b64 v[128:131], v236 offset1:80
	s_nop 0
	s_nop 0
	v_cvt_f16_f32_e32 v36, v40
	ds_read_b128 v[136:139], v180
	v_cvt_f16_f32_e32 v40, v42
	v_mfma_f32_16x16x16_f16 v[48:51], v[0:1], v[132:133], v[76:79]
	v_cvt_pk_f16_f32 v1, v46, v47
	v_cvt_pk_f16_f32 v0, v44, v45
	v_cvt_f16_f32_e32 v37, v41
	s_nop 0
	s_nop 0
	s_nop 2
	v_cvt_pk_f16_f32 v77, v50, v51
	v_cvt_pk_f16_f32 v76, v48, v49
	v_cndmask_b32_e64 v88, v40, 0, s[18:19]
	v_mfma_f32_16x16x32_f16 v[56:59], v[72:75], v[56:59], 0
	v_cndmask_b32_e64 v36, v36, 0, s[12:13]
	v_cndmask_b32_e64 v37, 0, v37, s[10:11]
	s_nop 0
	v_mfma_f32_16x16x16_f16 v[44:47], v[0:1], v[76:77], 0
	ds_read_b64 v[76:77], v222 offset:5120
	ds_read_b128 v[140:143], v180 offset:64
	s_nop 0
	s_waitcnt lgkmcnt(4)
	v_mfma_f32_16x16x32_f16 v[56:59], v[68:71], v[64:67], v[56:59]
	s_nop 5
	v_cvt_pk_f16_f32 v1, v46, v47
	v_cvt_pk_f16_f32 v0, v44, v45
	s_nop 0
	s_nop 0
	s_nop 0
	s_nop 0
	s_waitcnt lgkmcnt(3)
	s_nop 0
	s_nop 0
	ds_read_b64 v[44:45], v223 offset:5120
	ds_read2_b64 v[144:147], v236 offset0:160 offset1:240
	s_nop 0
	s_waitcnt lgkmcnt(4)
	v_pk_mul_f32 v[50:51], v[22:23], v[138:139]
	v_pk_mul_f32 v[48:49], v[20:21], v[136:137]
	ds_read_b128 v[136:139], v180 offset:128
	s_nop 1
	v_mfma_f32_16x16x16_f16 v[48:51], v[128:129], v[0:1], v[48:51]
	v_cvt_f16_f32_e32 v80, v43
	v_cndmask_b32_e64 v89, v80, 0, s[22:23]
	s_nop 0
	s_waitcnt lgkmcnt(4)
	v_mfma_f32_16x16x16_f16 v[40:43], v[76:77], v[132:133], v[48:51]
	s_nop 3
	s_nop 0
	s_nop 0
	ds_read_b64 v[80:81], v224 offset:5120
	v_mov_b32_e32 v76, v130
	v_mov_b32_e32 v77, v131
	s_nop 0
	s_nop 0
	s_waitcnt lgkmcnt(4)
	v_pk_mul_f32 v[50:51], v[34:35], v[142:143]
	v_pk_mul_f32 v[48:49], v[32:33], v[140:141]
	s_nop 0
	ds_read_b128 v[128:131], v180 offset:192
	s_nop 0
	v_mfma_f32_16x16x16_f16 v[48:51], v[76:77], v[0:1], v[48:51]
	s_nop 0
	s_nop 0
	s_waitcnt lgkmcnt(3)
	s_nop 0
	v_mfma_f32_16x16x16_f16 v[48:51], v[44:45], v[132:133], v[48:51]
	s_nop 0
	s_nop 0
	s_nop 0
	v_pack_b32_f16 v77, v88, v89
	s_nop 0
	s_nop 0
	s_waitcnt lgkmcnt(2)
	v_pk_mul_f32 v[46:47], v[30:31], v[138:139]
	v_pk_mul_f32 v[44:45], v[28:29], v[136:137]
	s_nop 0
	v_pack_b32_f16 v76, v36, v37
	v_mfma_f32_16x16x16_f16 v[44:47], v[144:145], v[0:1], v[44:47]
	ds_read_b64 v[84:85], v225 offset:5120
	v_cndmask_b32_e64 v36, v52, 0, s[12:13]
	v_cvt_f16_f32_e32 v37, v53
	v_cndmask_b32_e64 v37, 0, v37, s[10:11]
	s_nop 0
	s_waitcnt lgkmcnt(2)
	v_mfma_f32_16x16x16_f16 v[44:47], v[80:81], v[132:133], v[44:47]
	s_nop 0
	s_nop 0
	v_pack_b32_f16 v72, v36, v37
	ds_read_b128 v[68:71], v226 offset:9216
	ds_read_b128 v[94:97], v226 offset:9280
	s_nop 0
	s_waitcnt lgkmcnt(3)
	v_pk_mul_f32 v[82:83], v[26:27], v[130:131]
	ds_read_b128 v[64:67], v226 offset:18432
	v_pk_mul_f32 v[80:81], v[24:25], v[128:129]
	s_nop 0
	ds_read_b128 v[98:101], v226 offset:23104
	v_mfma_f32_16x16x16_f16 v[78:81], v[146:147], v[0:1], v[80:83]
	ds_read_b128 v[90:93], v226 offset:18496
	s_nop 1
	v_cvt_f16_f32_e32 v82, v54
	v_cvt_f16_f32_e32 v83, v55
	s_nop 0
	s_waitcnt lgkmcnt(5)
	v_mfma_f32_16x16x16_f16 v[52:55], v[84:85], v[132:133], v[78:81]
	ds_read_b128 v[86:89], v226 offset:13824
	s_nop 1
	v_cndmask_b32_e64 v78, v82, 0, s[18:19]
	v_cndmask_b32_e64 v79, v83, 0, s[22:23]
	v_pack_b32_f16 v73, v78, v79
	s_nop 0
	s_nop 0
	v_add_u32_e32 v80, s77, v122
	v_add_u32_e32 v81, s76, v235
	v_mfma_f32_16x16x16_f16 v[56:59], v[76:77], v[0:1], v[56:59]
	ds_read_b128 v[76:79], v226 offset:23040
	v_subrev_u32_e32 v102, 64, v80
	v_add_u32_e32 v0, 0xff, v81
	v_mfma_f32_16x16x16_f16 v[58:61], v[72:73], v[132:133], v[56:59]
	v_cndmask_b32_e64 v0, v0, v102, s[2:3]
	v_add_u32_e32 v0, v0, v173
	s_not_b32 s30, s2
	s_xor_b32 s31, s91, s30
	s_sub_u32 s31, s31, s30
	v_mad_i64_i32 v[0:1], s[28:29], v0, s91, v[126:127]
	v_mov_b64_e32 v[248:249], v[0:1]
	s_nop 0
	s_waitcnt lgkmcnt(4)
	v_mfma_f32_16x16x32_f16 v[82:85], v[68:71], v[64:67], 0
	s_nop 2
	v_cvt_f16_f32_e32 v2, v58
	v_cvt_f16_f32_e32 v60, v60
	ds_read_b128 v[128:131], v226 offset:13888
	global_store_short v[0:1], v2, off
	s_nop 0
	s_nop 0
	v_cvt_f16_f32_e32 v2, v59
	s_nop 0
	v_mfma_f32_16x16x32_f16 v[72:75], v[64:67], v[68:71], 0
	s_nop 0
	s_nop 0
	s_mul_i32 s52, s31, 1
	s_mul_hi_i32 s53, s31, 1
	v_lshl_add_u64 v[0:1], v[248:249], 0, s[52:53]
	s_nop 0
	s_waitcnt lgkmcnt(2)
	v_mfma_f32_16x16x32_f16 v[62:65], v[64:67], v[86:89], 0
	global_store_short v[0:1], v2, off
	s_nop 0
	s_nop 0
	v_mfma_f32_16x16x32_f16 v[82:85], v[94:97], v[90:93], v[82:85]
	s_nop 0
	s_nop 0
	s_nop 0
	s_waitcnt lgkmcnt(1)
	v_mfma_f32_16x16x32_f16 v[68:71], v[76:79], v[68:71], 0
	v_mfma_f32_16x16x32_f16 v[86:89], v[76:79], v[86:89], 0
	s_nop 2
	v_cvt_f16_f32_e32 v1, v82
	v_cvt_f16_f32_e32 v2, v83
	v_cvt_f16_f32_e32 v66, v85
	v_mfma_f32_16x16x32_f16 v[72:75], v[90:93], v[94:97], v[72:75]
	s_nop 0
	v_cndmask_b32_e64 v66, 0, v66, s[22:23]
	s_nop 0
	s_waitcnt lgkmcnt(0)
	v_mfma_f32_16x16x32_f16 v[76:79], v[90:93], v[128:131], v[62:65]
	s_nop 0
	s_nop 2
	v_cndmask_b32_e64 v0, 0, v72, s[10:11]
	v_cndmask_b32_e64 v37, 0, v73, s[14:15]
	v_cvt_f16_f32_e32 v63, v84
	v_mfma_f32_16x16x32_f16 v[94:97], v[98:101], v[94:97], v[68:71]
	v_cndmask_b32_e64 v64, 0, v74, s[16:17]
	v_cndmask_b32_e64 v65, 0, v75, s[20:21]
	v_cndmask_b32_e64 v63, 0, v63, s[18:19]
	v_cndmask_b32_e64 v68, 0, v1, s[12:13]
	v_cndmask_b32_e64 v69, v2, 0, s[10:11]
	v_add_f32_e32 v62, v215, v0
	v_cvt_pk_f16_f32 v1, v64, v65
	v_cvt_pk_f16_f32 v0, v0, v37
	s_nop 0
	v_pack_b32_f16 v67, v63, v66
	v_pack_b32_f16 v66, v68, v69
	s_nop 0
	s_nop 0
	v_add_f32_e32 v63, v217, v37
	v_add_f32_e32 v64, v218, v64
	v_mfma_f32_16x16x16_f16 v[70:73], v[0:1], v[66:67], 0
	v_add_f32_e32 v65, v219, v65
	v_cvt_pk_f16_f32 v83, v64, v65
	v_cvt_pk_f16_f32 v82, v62, v63
	v_mfma_f32_16x16x16_f16 v[66:69], v[66:67], v[0:1], 0
	s_nop 0
	s_nop 2
	v_cvt_pk_f16_f32 v0, v70, v71
	s_nop 0
	s_nop 0
	v_cvt_pk_f16_f32 v1, v72, v73
	v_cvt_pk_f16_f32 v69, v68, v69
	v_cvt_pk_f16_f32 v68, v66, v67
	v_mfma_f32_16x16x16_f16 v[62:65], v[0:1], v[82:83], v[62:65]
	s_mul_i32 s52, s31, 2
	s_mul_hi_i32 s53, s31, 2
	v_lshl_add_u64 v[36:37], v[248:249], 0, s[52:53]
	global_store_short v[36:37], v60, off
	v_mfma_f32_16x16x16_f16 v[72:75], v[68:69], v[0:1], 0
	v_cvt_f16_f32_e32 v82, v61
	v_subrev_u32_e32 v36, 61, v80
	v_xad_u32 v37, v102, -4, v166
	v_mfma_f32_16x16x16_f16 v[66:69], v[0:1], v[68:69], 0
	s_nop 0
	v_cvt_pk_f16_f32 v71, v64, v65
	s_nop 1
	v_cvt_pk_f16_f32 v1, v74, v75
	v_cvt_pk_f16_f32 v0, v72, v73
	ds_read2_b64 v[136:139], v227 offset1:4
	v_mfma_f32_16x16x32_f16 v[56:59], v[98:101], v[128:131], v[86:89]
	v_cvt_pk_f16_f32 v70, v62, v63
	s_nop 0
	s_nop 0
	v_cvt_pk_f16_f32 v85, v68, v69
	ds_read2_b64 v[128:131], v227 offset0:8 offset1:12
	v_cvt_pk_f16_f32 v84, v66, v67
	s_nop 0
	s_nop 0
	v_mfma_f32_16x16x16_f16 v[88:91], v[0:1], v[70:71], v[62:65]
	s_nop 0
	s_nop 0
	v_cndmask_b32_e64 v36, v37, v36, s[2:3]
	v_mfma_f32_16x16x16_f16 v[60:63], v[84:85], v[0:1], 0
	v_add_u32_e32 v83, v36, v173
	s_nop 2
	v_cvt_pk_f16_f32 v1, v90, v91
	v_cvt_pk_f16_f32 v0, v88, v89
	v_cvt_pk_f16_f32 v67, v54, v55
	v_cvt_pk_f16_f32 v66, v52, v53
	v_cvt_pk_f16_f32 v85, v62, v63
	v_cvt_pk_f16_f32 v84, v60, v61
	v_cvt_pk_f16_f32 v63, v50, v51
	v_cvt_pk_f16_f32 v62, v48, v49
	v_cvt_pk_f16_f32 v61, v42, v43
	v_cvt_pk_f16_f32 v60, v40, v41
	v_cvt_pk_f16_f32 v65, v46, v47
	v_cvt_pk_f16_f32 v64, v44, v45
	s_nop 0
	s_waitcnt lgkmcnt(1)
	v_mfma_f32_16x16x32_f16 v[68:71], v[136:139], v[60:63], 0
	v_add_u32_e32 v36, 0x1000, v227
	s_nop 0
	v_cvt_f16_f32_e32 v76, v76
	s_nop 0
	s_waitcnt lgkmcnt(0)
	v_mfma_f32_16x16x32_f16 v[98:101], v[128:131], v[64:67], v[68:71]
	ds_read2_b64 v[72:75], v36 offset0:64 offset1:68
	s_nop 1
	ds_read2_b64 v[68:71], v36 offset0:72 offset1:76
	v_cvt_f16_f32_e32 v36, v97
	v_cvt_f16_f32_e32 v97, v77
	v_mfma_f32_16x16x16_f16 v[84:87], v[84:85], v[0:1], v[88:91]
	v_cvt_f16_f32_e32 v0, v94
	v_cvt_f16_f32_e32 v1, v95
	v_cvt_f16_f32_e32 v2, v96
	v_cndmask_b32_e64 v96, v76, 0, s[12:13]
	v_cndmask_b32_e64 v0, 0, v0, s[10:11]
	v_cndmask_b32_e64 v37, 0, v1, s[14:15]
	v_cndmask_b32_e64 v1, 0, v2, s[16:17]
	v_cndmask_b32_e64 v2, 0, v36, s[20:21]
	v_pack_b32_f16 v1, v1, v2
	v_pack_b32_f16 v0, v0, v37
	s_nop 0
	v_mov_b32_e32 v36, v134
	v_mov_b32_e32 v37, v135
	s_nop 0
	s_nop 0
	v_mov_b32_e32 v94, v3
	v_mov_b32_e32 v95, v3
	v_mfma_f32_16x16x16_f16 v[88:91], v[0:1], v[134:135], v[98:101]
	v_cvt_pk_f16_f32 v1, v86, v87
	v_cvt_pk_f16_f32 v0, v84, v85
	v_cvt_f16_f32_e32 v56, v56
	v_cvt_f16_f32_e32 v98, v78
	v_cvt_f16_f32_e32 v99, v79
	s_nop 2
	v_cvt_pk_f16_f32 v91, v90, v91
	v_cvt_pk_f16_f32 v90, v88, v89
	v_cndmask_b32_e64 v97, 0, v97, s[10:11]
	v_cndmask_b32_e64 v98, v98, 0, s[18:19]
	v_mfma_f32_16x16x16_f16 v[84:87], v[0:1], v[90:91], 0
	v_add_u32_e32 v2, 0x800, v236
	ds_read2_b64 v[128:131], v2 offset0:64 offset1:144
	ds_read_b128 v[76:79], v180 offset:256
	v_mov_b32_e32 v90, v3
	v_mov_b32_e32 v91, v3
	v_cndmask_b32_e64 v99, v99, 0, s[22:23]
	ds_read_b64 v[88:89], v228 offset:5120
	ds_read_b128 v[132:135], v180 offset:320
	s_nop 3
	v_cvt_pk_f16_f32 v1, v86, v87
	v_cvt_pk_f16_f32 v0, v84, v85
	s_nop 0
	s_nop 0
	s_nop 0
	s_nop 0
	s_nop 0
	s_waitcnt lgkmcnt(3)
	s_nop 0
	s_nop 0
	ds_read_b64 v[84:85], v229 offset:5120
	s_nop 0
	s_waitcnt lgkmcnt(3)
	v_pk_mul_f32 v[42:43], v[42:43], v[78:79]
	v_pk_mul_f32 v[40:41], v[40:41], v[76:77]
	s_nop 0
	s_nop 0
	v_mfma_f32_16x16x16_f16 v[40:43], v[128:129], v[0:1], v[40:43]
	s_nop 0
	s_waitcnt lgkmcnt(1)
	v_pk_mul_f32 v[48:49], v[48:49], v[132:133]
	v_add_u32_e32 v76, 0xc00, v236
	ds_read2_b64 v[136:139], v76 offset0:96 offset1:176
	ds_read_b128 v[140:143], v180 offset:384
	v_mfma_f32_16x16x16_f16 v[40:43], v[88:89], v[36:37], v[40:43]
	s_nop 0
	s_nop 0
	v_pk_mul_f32 v[50:51], v[50:51], v[134:135]
	s_nop 0
	s_nop 0
	s_nop 0
	v_mfma_f32_16x16x16_f16 v[48:51], v[130:131], v[0:1], v[48:51]
	ds_read_b64 v[88:89], v230 offset:5120
	s_nop 0
	s_waitcnt lgkmcnt(2)
	s_nop 0
	v_mfma_f32_16x16x16_f16 v[48:51], v[84:85], v[36:37], v[48:51]
	s_nop 0
	s_nop 0
	s_nop 0
	v_pack_b32_f16 v76, v96, v97
	v_cndmask_b32_e64 v96, v56, 0, s[12:13]
	s_nop 0
	s_waitcnt lgkmcnt(1)
	v_pk_mul_f32 v[46:47], v[46:47], v[142:143]
	v_pk_mul_f32 v[44:45], v[44:45], v[140:141]
	ds_read_b128 v[84:87], v180 offset:448
	v_cvt_f16_f32_e32 v56, v57
	v_cvt_f16_f32_e32 v57, v58
	v_mfma_f32_16x16x16_f16 v[44:47], v[136:137], v[0:1], v[44:47]
	v_cvt_f16_f32_e32 v58, v59
	v_mov_b32_e32 v92, v138
	v_mov_b32_e32 v93, v139
	s_nop 0
	s_waitcnt lgkmcnt(1)
	v_mfma_f32_16x16x16_f16 v[44:47], v[88:89], v[36:37], v[44:47]
	ds_read_b64 v[88:89], v231 offset:5120
	s_nop 0
	s_nop 0
	v_cndmask_b32_e64 v78, v57, 0, s[18:19]
	v_cndmask_b32_e64 v79, v58, 0, s[22:23]
	v_pack_b32_f16 v77, v98, v99
	s_nop 0
	s_waitcnt lgkmcnt(1)
	v_pk_mul_f32 v[52:53], v[52:53], v[84:85]
	v_cndmask_b32_e64 v84, 0, v56, s[10:11]
	v_mfma_f32_16x16x32_f16 v[56:59], v[72:75], v[60:63], 0
	v_pack_b32_f16 v61, v78, v79
	v_mov_b32_e32 v78, v3
	v_mov_b32_e32 v79, v3
	v_mfma_f32_16x16x32_f16 v[56:59], v[68:71], v[64:67], v[56:59]
	v_mul_f32_e64 v54, v54, v86
	v_mul_f32_e64 v55, v55, v87
	v_pack_b32_f16 v60, v96, v84
	s_nop 0
	s_nop 0
	v_mfma_f32_16x16x16_f16 v[52:55], v[138:139], v[0:1], v[52:55]
	v_mfma_f32_16x16x16_f16 v[56:59], v[76:77], v[0:1], v[56:59]
	s_mul_i32 s52, s31, 3
	s_mul_hi_i32 s53, s31, 3
	v_lshl_add_u64 v[0:1], v[248:249], 0, s[52:53]
	global_store_short v[0:1], v82, off
	s_nop 0
	s_waitcnt lgkmcnt(0)
	v_mfma_f32_16x16x16_f16 v[52:55], v[88:89], v[36:37], v[52:55]
	s_nop 0
	s_nop 0
	s_nop 0
	v_mfma_f32_16x16x16_f16 v[36:39], v[60:61], v[36:37], v[56:59]
	s_nop 0
	s_mul_i32 s52, s31, 16
	s_mul_hi_i32 s53, s31, 16
	v_lshl_add_u64 v[0:1], v[248:249], 0, s[52:53]
	s_nop 5
	v_cvt_f16_f32_e32 v2, v36
	global_store_short v[0:1], v2, off
	s_nop 0
	s_nop 0
	v_cvt_f16_f32_e32 v2, v37
	s_nop 0
	s_nop 0
	s_mul_i32 s52, s31, 17
	s_mul_hi_i32 s53, s31, 17
	v_lshl_add_u64 v[0:1], v[248:249], 0, s[52:53]
	global_store_short v[0:1], v2, off
	s_nop 0
	s_nop 0
	v_cvt_f16_f32_e32 v2, v38
	s_nop 0
	s_nop 0
	s_mul_i32 s52, s31, 18
	s_mul_hi_i32 s53, s31, 18
	v_lshl_add_u64 v[0:1], v[248:249], 0, s[52:53]
	global_store_short v[0:1], v2, off
	s_nop 0
	s_nop 0
	s_nop 0
	v_cvt_f16_f32_e32 v2, v39
	s_nop 0
	s_mul_i32 s52, s31, 19
	s_mul_hi_i32 s53, s31, 19
	v_lshl_add_u64 v[0:1], v[248:249], 0, s[52:53]
	s_mov_b64 s[28:29], 0
	global_store_short v[0:1], v2, off

.LBB0_462:
	s_or_b64 exec, exec, s[26:27]
	s_waitcnt lgkmcnt(0)
	s_barrier
	ds_read_b128 v[40:43], v210 offset:9216
	ds_read_b128 v[48:51], v210 offset:18496
	ds_read_b128 v[56:59], v210 offset:9280
	ds_read_b128 v[60:63], v210 offset:23040
	ds_read_b128 v[36:39], v210 offset:18432
	s_nop 0
	s_nop 0
	s_nop 0
	ds_read_b128 v[64:67], v210 offset:13824
	s_waitcnt lgkmcnt(1)
	v_mfma_f32_16x16x32_f16 v[52:55], v[40:43], v[36:39], 0
	s_nop 0
	s_nop 0
	s_nop 0
	ds_read_b128 v[68:71], v210 offset:13888
	ds_read_b128 v[72:75], v210 offset:23104
	v_add_u32_e32 v80, 0x1000, v215
	s_nop 0
	v_mfma_f32_16x16x32_f16 v[52:55], v[56:59], v[48:51], v[52:55]
	s_nop 0
	s_nop 0
	s_nop 0
	v_mfma_f32_16x16x32_f16 v[44:47], v[36:39], v[40:43], 0
	s_nop 3
	v_cvt_f16_f32_e32 v0, v52
	v_cvt_f16_f32_e32 v1, v54
	v_cvt_f16_f32_e32 v2, v55
	v_mfma_f32_16x16x32_f16 v[44:47], v[48:51], v[56:59], v[44:47]
	v_cndmask_b32_e64 v79, 0, v0, s[12:13]
	v_cvt_f16_f32_e32 v0, v53
	v_cndmask_b32_e64 v54, 0, v1, s[18:19]
	s_nop 0
	v_mfma_f32_16x16x32_f16 v[40:43], v[60:63], v[40:43], 0
	v_cndmask_b32_e64 v55, 0, v2, s[22:23]
	s_nop 1
	v_cndmask_b32_e64 v76, 0, v44, s[10:11]
	v_cndmask_b32_e64 v77, 0, v45, s[14:15]
	s_nop 0
	s_waitcnt lgkmcnt(2)
	v_mfma_f32_16x16x32_f16 v[36:39], v[36:39], v[64:67], 0
	v_cndmask_b32_e64 v52, 0, v46, s[16:17]
	v_cndmask_b32_e64 v78, 0, v47, s[20:21]
	v_cndmask_b32_e64 v53, v0, 0, s[10:11]
	v_mfma_f32_16x16x32_f16 v[44:47], v[60:63], v[64:67], 0
	v_cvt_pk_f16_f32 v1, v52, v78
	v_cvt_pk_f16_f32 v0, v76, v77
	s_nop 0
	s_nop 0
	s_waitcnt lgkmcnt(0)
	v_mfma_f32_16x16x32_f16 v[60:63], v[72:75], v[56:59], v[40:43]
	v_add_f32_e32 v56, v211, v76
	v_add_f32_e32 v57, v212, v77
	v_add_f32_e32 v58, v213, v52
	v_mfma_f32_16x16x32_f16 v[40:43], v[48:51], v[68:71], v[36:39]
	v_add_f32_e32 v59, v214, v78
	v_cvt_pk_f16_f32 v67, v18, v19
	v_cvt_pk_f16_f32 v66, v16, v17
	v_pack_b32_f16 v37, v54, v55
	v_pack_b32_f16 v36, v79, v53
	s_nop 0
	s_nop 0
	v_mfma_f32_16x16x32_f16 v[52:55], v[72:75], v[68:71], v[44:47]
	ds_read2_b64 v[68:71], v215 offset0:8 offset1:12
	v_cvt_pk_f16_f32 v65, v14, v15
	v_cvt_pk_f16_f32 v64, v12, v13
	v_mfma_f32_16x16x16_f16 v[48:51], v[0:1], v[36:37], 0
	v_cvt_pk_f16_f32 v45, v58, v59
	v_cvt_pk_f16_f32 v44, v56, v57
	s_nop 0
	v_mfma_f32_16x16x16_f16 v[36:39], v[36:37], v[0:1], 0
	s_nop 0
	s_nop 2
	v_cvt_pk_f16_f32 v1, v50, v51
	v_cvt_pk_f16_f32 v0, v48, v49
	s_nop 0
	s_nop 0
	v_cvt_pk_f16_f32 v49, v38, v39
	v_cvt_pk_f16_f32 v48, v36, v37
	v_mfma_f32_16x16x16_f16 v[44:47], v[0:1], v[44:45], v[56:59]
	s_nop 0
	s_nop 0
	s_nop 0
	v_mfma_f32_16x16x16_f16 v[36:39], v[48:49], v[0:1], 0
	ds_read2_b64 v[126:129], v215 offset1:4
	v_cvt_pk_f16_f32 v59, v10, v11
	v_cvt_pk_f16_f32 v58, v8, v9
	v_cvt_pk_f16_f32 v57, v6, v7
	v_mfma_f32_16x16x16_f16 v[48:51], v[0:1], v[48:49], 0
	v_cvt_pk_f16_f32 v56, v4, v5
	s_nop 2
	v_cvt_pk_f16_f32 v1, v38, v39
	v_cvt_pk_f16_f32 v0, v36, v37
	v_cvt_pk_f16_f32 v37, v46, v47
	v_cvt_pk_f16_f32 v36, v44, v45
	s_nop 0
	s_nop 0
	v_cvt_f16_f32_e32 v52, v52
	s_add_i32 s28, s76, 1
	v_mfma_f32_16x16x16_f16 v[44:47], v[0:1], v[36:37], v[44:47]
	v_cvt_pk_f16_f32 v37, v50, v51
	v_cvt_pk_f16_f32 v36, v48, v49
	s_nop 0
	s_nop 0
	v_mfma_f32_16x16x16_f16 v[36:39], v[36:37], v[0:1], 0
	s_nop 2
	v_cvt_pk_f16_f32 v1, v46, v47
	v_cvt_pk_f16_f32 v0, v44, v45
	s_nop 2
	v_cvt_pk_f16_f32 v49, v38, v39
	v_cvt_pk_f16_f32 v48, v36, v37
	s_nop 0
	s_nop 0
	s_waitcnt lgkmcnt(0)
	v_mfma_f32_16x16x32_f16 v[36:39], v[126:129], v[56:59], 0
	v_mfma_f32_16x16x16_f16 v[44:47], v[48:49], v[0:1], v[44:47]
	v_cvt_f16_f32_e32 v0, v60
	v_cvt_f16_f32_e32 v1, v61
	v_cvt_f16_f32_e32 v2, v62
	v_cvt_f16_f32_e32 v48, v63
	v_mfma_f32_16x16x32_f16 v[76:79], v[68:71], v[64:67], v[36:39]
	ds_read2_b64 v[72:75], v80 offset0:64 offset1:68
	ds_read2st64_b64 v[130:133], v216 offset0:20 offset1:25
	ds_read2_b64 v[68:71], v80 offset0:72 offset1:76
	s_nop 0
	s_nop 0
	v_cndmask_b32_e64 v0, 0, v0, s[10:11]
	v_cndmask_b32_e64 v49, 0, v1, s[14:15]
	v_cndmask_b32_e64 v1, 0, v2, s[16:17]
	v_cndmask_b32_e64 v2, 0, v48, s[20:21]
	v_pack_b32_f16 v1, v1, v2
	v_pack_b32_f16 v0, v0, v49
	s_nop 0
	s_nop 0
	s_waitcnt lgkmcnt(1)
	s_nop 0
	s_nop 0
	ds_read2_b64 v[126:129], v231 offset1:80
	s_nop 0
	s_nop 0
	v_cvt_f16_f32_e32 v36, v40
	ds_read_b128 v[134:137], v176
	v_cvt_f16_f32_e32 v40, v42
	v_mfma_f32_16x16x16_f16 v[48:51], v[0:1], v[130:131], v[76:79]
	v_cvt_pk_f16_f32 v1, v46, v47
	v_cvt_pk_f16_f32 v0, v44, v45
	v_cvt_f16_f32_e32 v37, v41
	s_nop 0
	s_nop 0
	s_nop 2
	v_cvt_pk_f16_f32 v77, v50, v51
	v_cvt_pk_f16_f32 v76, v48, v49
	v_cndmask_b32_e64 v88, v40, 0, s[18:19]
	v_mfma_f32_16x16x32_f16 v[56:59], v[72:75], v[56:59], 0
	v_cndmask_b32_e64 v36, v36, 0, s[12:13]
	v_cndmask_b32_e64 v37, 0, v37, s[10:11]
	s_nop 0
	v_mfma_f32_16x16x16_f16 v[44:47], v[0:1], v[76:77], 0
	ds_read_b64 v[76:77], v217 offset:5120
	ds_read_b128 v[138:141], v176 offset:64
	s_nop 0
	s_waitcnt lgkmcnt(4)
	v_mfma_f32_16x16x32_f16 v[56:59], v[68:71], v[64:67], v[56:59]
	s_nop 5
	v_cvt_pk_f16_f32 v1, v46, v47
	v_cvt_pk_f16_f32 v0, v44, v45
	s_nop 0
	s_nop 0
	s_nop 0
	s_nop 0
	s_waitcnt lgkmcnt(3)
	s_nop 0
	s_nop 0
	ds_read_b64 v[44:45], v218 offset:5120
	ds_read2_b64 v[142:145], v231 offset0:160 offset1:240
	s_nop 0
	s_waitcnt lgkmcnt(4)
	v_pk_mul_f32 v[50:51], v[6:7], v[136:137]
	v_pk_mul_f32 v[48:49], v[4:5], v[134:135]
	ds_read_b128 v[134:137], v176 offset:128
	s_nop 1
	v_mfma_f32_16x16x16_f16 v[48:51], v[126:127], v[0:1], v[48:51]
	v_cvt_f16_f32_e32 v80, v43
	v_cndmask_b32_e64 v89, v80, 0, s[22:23]
	s_nop 0
	s_waitcnt lgkmcnt(4)
	v_mfma_f32_16x16x16_f16 v[40:43], v[76:77], v[130:131], v[48:51]
	s_nop 3
	s_nop 0
	s_nop 0
	ds_read_b64 v[80:81], v219 offset:5120
	v_mov_b32_e32 v76, v128
	v_mov_b32_e32 v77, v129
	s_nop 0
	s_nop 0
	s_waitcnt lgkmcnt(4)
	v_pk_mul_f32 v[50:51], v[10:11], v[140:141]
	v_pk_mul_f32 v[48:49], v[8:9], v[138:139]
	s_nop 0
	ds_read_b128 v[126:129], v176 offset:192
	s_nop 0
	v_mfma_f32_16x16x16_f16 v[48:51], v[76:77], v[0:1], v[48:51]
	s_nop 0
	s_nop 0
	s_waitcnt lgkmcnt(3)
	s_nop 0
	v_mfma_f32_16x16x16_f16 v[48:51], v[44:45], v[130:131], v[48:51]
	s_nop 0
	s_nop 0
	s_nop 0
	v_pack_b32_f16 v77, v88, v89
	s_nop 0
	s_nop 0
	s_waitcnt lgkmcnt(2)
	v_pk_mul_f32 v[46:47], v[14:15], v[136:137]
	v_pk_mul_f32 v[44:45], v[12:13], v[134:135]
	s_nop 0
	v_pack_b32_f16 v76, v36, v37
	v_mfma_f32_16x16x16_f16 v[44:47], v[142:143], v[0:1], v[44:47]
	ds_read_b64 v[84:85], v220 offset:5120
	v_cndmask_b32_e64 v36, v52, 0, s[12:13]
	v_cvt_f16_f32_e32 v37, v53
	v_cndmask_b32_e64 v37, 0, v37, s[10:11]
	s_nop 0
	s_waitcnt lgkmcnt(2)
	v_mfma_f32_16x16x16_f16 v[44:47], v[80:81], v[130:131], v[44:47]
	s_nop 0
	s_nop 0
	v_pack_b32_f16 v72, v36, v37
	ds_read_b128 v[68:71], v221 offset:9216
	ds_read_b128 v[94:97], v221 offset:9280
	s_nop 0
	s_waitcnt lgkmcnt(3)
	v_pk_mul_f32 v[82:83], v[18:19], v[128:129]
	ds_read_b128 v[64:67], v221 offset:18432
	v_pk_mul_f32 v[80:81], v[16:17], v[126:127]
	s_nop 0
	ds_read_b128 v[98:101], v221 offset:23104
	v_mfma_f32_16x16x16_f16 v[78:81], v[144:145], v[0:1], v[80:83]
	ds_read_b128 v[90:93], v221 offset:18496
	s_nop 1
	v_cvt_f16_f32_e32 v82, v54
	v_cvt_f16_f32_e32 v83, v55
	s_nop 0
	s_waitcnt lgkmcnt(5)
	v_mfma_f32_16x16x16_f16 v[52:55], v[84:85], v[130:131], v[78:81]
	ds_read_b128 v[86:89], v221 offset:13824
	s_nop 1
	v_cndmask_b32_e64 v78, v82, 0, s[18:19]
	v_cndmask_b32_e64 v79, v83, 0, s[22:23]
	v_pack_b32_f16 v73, v78, v79
	s_nop 0
	s_nop 0
	v_add_u32_e32 v80, s71, v153
	v_add_u32_e32 v81, s70, v230
	v_mfma_f32_16x16x16_f16 v[56:59], v[76:77], v[0:1], v[56:59]
	ds_read_b128 v[76:79], v221 offset:23040
	v_subrev_u32_e32 v102, 64, v80
	v_add_u32_e32 v0, 0x7ff, v81
	v_mfma_f32_16x16x16_f16 v[58:61], v[72:73], v[130:131], v[56:59]
	v_cndmask_b32_e64 v0, v0, v102, s[2:3]
	v_add_u32_e32 v0, v0, v151
	s_not_b32 s30, s2
	s_xor_b32 s31, s91, s30
	s_sub_u32 s31, s31, s30
	v_mad_i64_i32 v[0:1], s[26:27], v0, s91, v[122:123]
	v_mov_b64_e32 v[248:249], v[0:1]
	s_nop 0
	s_waitcnt lgkmcnt(4)
	v_mfma_f32_16x16x32_f16 v[82:85], v[68:71], v[64:67], 0
	s_nop 2
	v_cvt_f16_f32_e32 v2, v58
	v_cvt_f16_f32_e32 v60, v60
	ds_read_b128 v[126:129], v221 offset:13888
	global_store_short v[0:1], v2, off
	s_nop 0
	s_nop 0
	v_cvt_f16_f32_e32 v2, v59
	s_nop 0
	v_mfma_f32_16x16x32_f16 v[72:75], v[64:67], v[68:71], 0
	s_nop 0
	s_nop 0
	s_mul_i32 s52, s31, 1
	s_mul_hi_i32 s53, s31, 1
	v_lshl_add_u64 v[0:1], v[248:249], 0, s[52:53]
	s_nop 0
	s_waitcnt lgkmcnt(2)
	v_mfma_f32_16x16x32_f16 v[62:65], v[64:67], v[86:89], 0
	global_store_short v[0:1], v2, off
	s_nop 0
	s_nop 0
	v_mfma_f32_16x16x32_f16 v[82:85], v[94:97], v[90:93], v[82:85]
	s_nop 0
	s_nop 0
	s_nop 0
	s_waitcnt lgkmcnt(1)
	v_mfma_f32_16x16x32_f16 v[68:71], v[76:79], v[68:71], 0
	v_mfma_f32_16x16x32_f16 v[86:89], v[76:79], v[86:89], 0
	s_nop 2
	v_cvt_f16_f32_e32 v1, v82
	v_cvt_f16_f32_e32 v2, v83
	v_cvt_f16_f32_e32 v66, v85
	v_mfma_f32_16x16x32_f16 v[72:75], v[90:93], v[94:97], v[72:75]
	s_nop 0
	v_cndmask_b32_e64 v66, 0, v66, s[22:23]
	s_nop 0
	s_waitcnt lgkmcnt(0)
	v_mfma_f32_16x16x32_f16 v[76:79], v[90:93], v[126:129], v[62:65]
	s_nop 0
	s_nop 2
	v_cndmask_b32_e64 v0, 0, v72, s[10:11]
	v_cndmask_b32_e64 v37, 0, v73, s[14:15]
	v_cvt_f16_f32_e32 v63, v84
	v_mfma_f32_16x16x32_f16 v[94:97], v[98:101], v[94:97], v[68:71]
	v_cndmask_b32_e64 v64, 0, v74, s[16:17]
	v_cndmask_b32_e64 v65, 0, v75, s[20:21]
	v_cndmask_b32_e64 v63, 0, v63, s[18:19]
	v_cndmask_b32_e64 v68, 0, v1, s[12:13]
	v_cndmask_b32_e64 v69, v2, 0, s[10:11]
	v_add_f32_e32 v62, v211, v0
	v_cvt_pk_f16_f32 v1, v64, v65
	v_cvt_pk_f16_f32 v0, v0, v37
	s_nop 0
	v_pack_b32_f16 v67, v63, v66
	v_pack_b32_f16 v66, v68, v69
	s_nop 0
	s_nop 0
	v_add_f32_e32 v63, v212, v37
	v_add_f32_e32 v64, v213, v64
	v_mfma_f32_16x16x16_f16 v[70:73], v[0:1], v[66:67], 0
	v_add_f32_e32 v65, v214, v65
	v_cvt_pk_f16_f32 v83, v64, v65
	v_cvt_pk_f16_f32 v82, v62, v63
	v_mfma_f32_16x16x16_f16 v[66:69], v[66:67], v[0:1], 0
	s_nop 0
	s_nop 2
	v_cvt_pk_f16_f32 v0, v70, v71
	s_nop 0
	s_nop 0
	v_cvt_pk_f16_f32 v1, v72, v73
	v_cvt_pk_f16_f32 v69, v68, v69
	v_cvt_pk_f16_f32 v68, v66, v67
	v_mfma_f32_16x16x16_f16 v[62:65], v[0:1], v[82:83], v[62:65]
	s_mul_i32 s52, s31, 2
	s_mul_hi_i32 s53, s31, 2
	v_lshl_add_u64 v[36:37], v[248:249], 0, s[52:53]
	global_store_short v[36:37], v60, off
	v_mfma_f32_16x16x16_f16 v[72:75], v[68:69], v[0:1], 0
	v_cvt_f16_f32_e32 v82, v61
	v_subrev_u32_e32 v36, 61, v80
	v_xad_u32 v37, v102, -4, v170
	v_mfma_f32_16x16x16_f16 v[66:69], v[0:1], v[68:69], 0
	s_nop 0
	v_cvt_pk_f16_f32 v71, v64, v65
	s_nop 1
	v_cvt_pk_f16_f32 v1, v74, v75
	v_cvt_pk_f16_f32 v0, v72, v73
	ds_read2_b64 v[134:137], v222 offset1:4
	v_mfma_f32_16x16x32_f16 v[56:59], v[98:101], v[126:129], v[86:89]
	v_cvt_pk_f16_f32 v70, v62, v63
	s_nop 0
	s_nop 0
	v_cvt_pk_f16_f32 v85, v68, v69
	ds_read2_b64 v[126:129], v222 offset0:8 offset1:12
	v_cvt_pk_f16_f32 v84, v66, v67
	s_nop 0
	s_nop 0
	v_mfma_f32_16x16x16_f16 v[88:91], v[0:1], v[70:71], v[62:65]
	s_nop 0
	s_nop 0
	v_cndmask_b32_e64 v36, v37, v36, s[2:3]
	v_mfma_f32_16x16x16_f16 v[60:63], v[84:85], v[0:1], 0
	v_add_u32_e32 v83, v36, v151
	s_nop 2
	v_cvt_pk_f16_f32 v1, v90, v91
	v_cvt_pk_f16_f32 v0, v88, v89
	v_cvt_pk_f16_f32 v67, v54, v55
	v_cvt_pk_f16_f32 v66, v52, v53
	v_cvt_pk_f16_f32 v85, v62, v63
	v_cvt_pk_f16_f32 v84, v60, v61
	v_cvt_pk_f16_f32 v63, v50, v51
	v_cvt_pk_f16_f32 v62, v48, v49
	v_cvt_pk_f16_f32 v61, v42, v43
	v_cvt_pk_f16_f32 v60, v40, v41
	v_cvt_pk_f16_f32 v65, v46, v47
	v_cvt_pk_f16_f32 v64, v44, v45
	s_nop 0
	s_waitcnt lgkmcnt(1)
	v_mfma_f32_16x16x32_f16 v[68:71], v[134:137], v[60:63], 0
	v_add_u32_e32 v36, 0x1000, v222
	s_nop 0
	v_cvt_f16_f32_e32 v76, v76
	s_nop 0
	s_waitcnt lgkmcnt(0)
	v_mfma_f32_16x16x32_f16 v[98:101], v[126:129], v[64:67], v[68:71]
	ds_read2_b64 v[72:75], v36 offset0:64 offset1:68
	s_nop 1
	ds_read2_b64 v[68:71], v36 offset0:72 offset1:76
	v_cvt_f16_f32_e32 v36, v97
	v_cvt_f16_f32_e32 v97, v77
	v_mfma_f32_16x16x16_f16 v[84:87], v[84:85], v[0:1], v[88:91]
	v_cvt_f16_f32_e32 v0, v94
	v_cvt_f16_f32_e32 v1, v95
	v_cvt_f16_f32_e32 v2, v96
	v_cndmask_b32_e64 v96, v76, 0, s[12:13]
	v_cndmask_b32_e64 v0, 0, v0, s[10:11]
	v_cndmask_b32_e64 v37, 0, v1, s[14:15]
	v_cndmask_b32_e64 v1, 0, v2, s[16:17]
	v_cndmask_b32_e64 v2, 0, v36, s[20:21]
	v_pack_b32_f16 v1, v1, v2
	v_pack_b32_f16 v0, v0, v37
	s_nop 0
	v_mov_b32_e32 v36, v132
	v_mov_b32_e32 v37, v133
	s_nop 0
	s_nop 0
	v_mov_b32_e32 v94, v3
	v_mov_b32_e32 v95, v3
	v_mfma_f32_16x16x16_f16 v[88:91], v[0:1], v[132:133], v[98:101]
	v_cvt_pk_f16_f32 v1, v86, v87
	v_cvt_pk_f16_f32 v0, v84, v85
	v_cvt_f16_f32_e32 v56, v56
	v_cvt_f16_f32_e32 v98, v78
	v_cvt_f16_f32_e32 v99, v79
	s_nop 2
	v_cvt_pk_f16_f32 v91, v90, v91
	v_cvt_pk_f16_f32 v90, v88, v89
	v_cndmask_b32_e64 v97, 0, v97, s[10:11]
	v_cndmask_b32_e64 v98, v98, 0, s[18:19]
	v_mfma_f32_16x16x16_f16 v[84:87], v[0:1], v[90:91], 0
	v_add_u32_e32 v2, 0x800, v231
	ds_read2_b64 v[126:129], v2 offset0:64 offset1:144
	ds_read_b128 v[76:79], v176 offset:256
	v_mov_b32_e32 v90, v3
	v_mov_b32_e32 v91, v3
	v_cndmask_b32_e64 v99, v99, 0, s[22:23]
	ds_read_b64 v[88:89], v223 offset:5120
	ds_read_b128 v[130:133], v176 offset:320
	s_nop 3
	v_cvt_pk_f16_f32 v1, v86, v87
	v_cvt_pk_f16_f32 v0, v84, v85
	s_nop 0
	s_nop 0
	s_nop 0
	s_nop 0
	s_nop 0
	s_waitcnt lgkmcnt(3)
	s_nop 0
	s_nop 0
	ds_read_b64 v[84:85], v224 offset:5120
	s_nop 0
	s_waitcnt lgkmcnt(3)
	v_pk_mul_f32 v[42:43], v[42:43], v[78:79]
	v_pk_mul_f32 v[40:41], v[40:41], v[76:77]
	s_nop 0
	s_nop 0
	v_mfma_f32_16x16x16_f16 v[40:43], v[126:127], v[0:1], v[40:43]
	s_nop 0
	s_waitcnt lgkmcnt(1)
	v_pk_mul_f32 v[48:49], v[48:49], v[130:131]
	v_add_u32_e32 v76, 0xc00, v231
	ds_read2_b64 v[134:137], v76 offset0:96 offset1:176
	ds_read_b128 v[138:141], v176 offset:384
	v_mfma_f32_16x16x16_f16 v[40:43], v[88:89], v[36:37], v[40:43]
	s_nop 0
	s_nop 0
	v_pk_mul_f32 v[50:51], v[50:51], v[132:133]
	s_nop 0
	s_nop 0
	s_nop 0
	v_mfma_f32_16x16x16_f16 v[48:51], v[128:129], v[0:1], v[48:51]
	ds_read_b64 v[88:89], v225 offset:5120
	s_nop 0
	s_waitcnt lgkmcnt(2)
	s_nop 0
	v_mfma_f32_16x16x16_f16 v[48:51], v[84:85], v[36:37], v[48:51]
	s_nop 0
	s_nop 0
	s_nop 0
	v_pack_b32_f16 v76, v96, v97
	v_cndmask_b32_e64 v96, v56, 0, s[12:13]
	s_nop 0
	s_waitcnt lgkmcnt(1)
	v_pk_mul_f32 v[46:47], v[46:47], v[140:141]
	v_pk_mul_f32 v[44:45], v[44:45], v[138:139]
	ds_read_b128 v[84:87], v176 offset:448
	v_cvt_f16_f32_e32 v56, v57
	v_cvt_f16_f32_e32 v57, v58
	v_mfma_f32_16x16x16_f16 v[44:47], v[134:135], v[0:1], v[44:47]
	v_cvt_f16_f32_e32 v58, v59
	v_mov_b32_e32 v92, v136
	v_mov_b32_e32 v93, v137
	s_nop 0
	s_waitcnt lgkmcnt(1)
	v_mfma_f32_16x16x16_f16 v[44:47], v[88:89], v[36:37], v[44:47]
	ds_read_b64 v[88:89], v226 offset:5120
	s_nop 0
	s_nop 0
	v_cndmask_b32_e64 v78, v57, 0, s[18:19]
	v_cndmask_b32_e64 v79, v58, 0, s[22:23]
	v_pack_b32_f16 v77, v98, v99
	s_nop 0
	s_waitcnt lgkmcnt(1)
	v_pk_mul_f32 v[52:53], v[52:53], v[84:85]
	v_cndmask_b32_e64 v84, 0, v56, s[10:11]
	v_mfma_f32_16x16x32_f16 v[56:59], v[72:75], v[60:63], 0
	v_pack_b32_f16 v61, v78, v79
	v_mov_b32_e32 v78, v3
	v_mov_b32_e32 v79, v3
	v_mfma_f32_16x16x32_f16 v[56:59], v[68:71], v[64:67], v[56:59]
	v_mul_f32_e64 v54, v54, v86
	v_mul_f32_e64 v55, v55, v87
	v_pack_b32_f16 v60, v96, v84
	s_nop 0
	s_nop 0
	v_mfma_f32_16x16x16_f16 v[52:55], v[136:137], v[0:1], v[52:55]
	v_mfma_f32_16x16x16_f16 v[56:59], v[76:77], v[0:1], v[56:59]
	s_mul_i32 s52, s31, 3
	s_mul_hi_i32 s53, s31, 3
	v_lshl_add_u64 v[0:1], v[248:249], 0, s[52:53]
	global_store_short v[0:1], v82, off
	s_nop 0
	s_waitcnt lgkmcnt(0)
	v_mfma_f32_16x16x16_f16 v[52:55], v[88:89], v[36:37], v[52:55]
	s_nop 0
	s_nop 0
	s_nop 0
	v_mfma_f32_16x16x16_f16 v[36:39], v[60:61], v[36:37], v[56:59]
	s_nop 0
	s_mul_i32 s52, s31, 16
	s_mul_hi_i32 s53, s31, 16
	v_lshl_add_u64 v[0:1], v[248:249], 0, s[52:53]
	s_nop 5
	v_cvt_f16_f32_e32 v2, v36
	global_store_short v[0:1], v2, off
	s_nop 0
	s_nop 0
	v_cvt_f16_f32_e32 v2, v37
	s_nop 0
	s_nop 0
	s_mul_i32 s52, s31, 17
	s_mul_hi_i32 s53, s31, 17
	v_lshl_add_u64 v[0:1], v[248:249], 0, s[52:53]
	global_store_short v[0:1], v2, off
	s_nop 0
	s_nop 0
	v_cvt_f16_f32_e32 v2, v38
	s_nop 0
	s_nop 0
	s_mul_i32 s52, s31, 18
	s_mul_hi_i32 s53, s31, 18
	v_lshl_add_u64 v[0:1], v[248:249], 0, s[52:53]
	global_store_short v[0:1], v2, off
	s_nop 0
	s_nop 0
	s_nop 0
	v_cvt_f16_f32_e32 v2, v39
	s_nop 0
	s_mul_i32 s52, s31, 19
	s_mul_hi_i32 s53, s31, 19
	v_lshl_add_u64 v[0:1], v[248:249], 0, s[52:53]
	s_mov_b64 s[26:27], 0
	global_store_short v[0:1], v2, off

.LBB0_935:
	s_or_b64 exec, exec, s[28:29]
	s_waitcnt lgkmcnt(0)
	s_barrier
	ds_read_b128 v[40:43], v216 offset:9216
	ds_read_b128 v[48:51], v216 offset:18496
	ds_read_b128 v[56:59], v216 offset:9280
	ds_read_b128 v[60:63], v216 offset:23040
	ds_read_b128 v[36:39], v216 offset:18432
	s_nop 0
	s_nop 0
	s_nop 0
	ds_read_b128 v[64:67], v216 offset:13824
	s_waitcnt lgkmcnt(1)
	v_mfma_f32_16x16x32_f16 v[52:55], v[40:43], v[36:39], 0
	s_nop 0
	s_nop 0
	s_nop 0
	ds_read_b128 v[68:71], v216 offset:13888
	ds_read_b128 v[72:75], v216 offset:23104
	v_add_u32_e32 v80, 0x1000, v222
	s_nop 0
	v_mfma_f32_16x16x32_f16 v[52:55], v[56:59], v[48:51], v[52:55]
	s_nop 0
	s_nop 0
	s_nop 0
	v_mfma_f32_16x16x32_f16 v[44:47], v[36:39], v[40:43], 0
	s_nop 3
	v_cvt_f16_f32_e32 v0, v52
	v_cvt_f16_f32_e32 v1, v54
	v_cvt_f16_f32_e32 v2, v55
	v_mfma_f32_16x16x32_f16 v[44:47], v[48:51], v[56:59], v[44:47]
	v_cndmask_b32_e64 v79, 0, v0, s[12:13]
	v_cvt_f16_f32_e32 v0, v53
	v_cndmask_b32_e64 v54, 0, v1, s[18:19]
	s_nop 0
	v_mfma_f32_16x16x32_f16 v[40:43], v[60:63], v[40:43], 0
	v_cndmask_b32_e64 v55, 0, v2, s[22:23]
	s_nop 1
	v_cndmask_b32_e64 v76, 0, v44, s[10:11]
	v_cndmask_b32_e64 v77, 0, v45, s[14:15]
	s_nop 0
	s_waitcnt lgkmcnt(2)
	v_mfma_f32_16x16x32_f16 v[36:39], v[36:39], v[64:67], 0
	v_cndmask_b32_e64 v52, 0, v46, s[16:17]
	v_cndmask_b32_e64 v78, 0, v47, s[20:21]
	v_cndmask_b32_e64 v53, v0, 0, s[10:11]
	v_mfma_f32_16x16x32_f16 v[44:47], v[60:63], v[64:67], 0
	v_cvt_pk_f16_f32 v1, v52, v78
	v_cvt_pk_f16_f32 v0, v76, v77
	s_nop 0
	s_nop 0
	s_waitcnt lgkmcnt(0)
	v_mfma_f32_16x16x32_f16 v[60:63], v[72:75], v[56:59], v[40:43]
	v_add_f32_e32 v56, v217, v76
	v_add_f32_e32 v57, v219, v77
	v_add_f32_e32 v58, v220, v52
	v_mfma_f32_16x16x32_f16 v[40:43], v[48:51], v[68:71], v[36:39]
	v_add_f32_e32 v59, v221, v78
	v_cvt_pk_f16_f32 v67, v26, v27
	v_cvt_pk_f16_f32 v66, v24, v25
	v_pack_b32_f16 v37, v54, v55
	v_pack_b32_f16 v36, v79, v53
	s_nop 0
	s_nop 0
	v_mfma_f32_16x16x32_f16 v[52:55], v[72:75], v[68:71], v[44:47]
	ds_read2_b64 v[68:71], v222 offset0:8 offset1:12
	v_cvt_pk_f16_f32 v65, v30, v31
	v_cvt_pk_f16_f32 v64, v28, v29
	v_mfma_f32_16x16x16_f16 v[48:51], v[0:1], v[36:37], 0
	v_cvt_pk_f16_f32 v45, v58, v59
	v_cvt_pk_f16_f32 v44, v56, v57
	s_nop 0
	v_mfma_f32_16x16x16_f16 v[36:39], v[36:37], v[0:1], 0
	s_nop 0
	s_nop 2
	v_cvt_pk_f16_f32 v1, v50, v51
	v_cvt_pk_f16_f32 v0, v48, v49
	s_nop 0
	s_nop 0
	v_cvt_pk_f16_f32 v49, v38, v39
	v_cvt_pk_f16_f32 v48, v36, v37
	v_mfma_f32_16x16x16_f16 v[44:47], v[0:1], v[44:45], v[56:59]
	s_nop 0
	s_nop 0
	s_nop 0
	v_mfma_f32_16x16x16_f16 v[36:39], v[48:49], v[0:1], 0
	ds_read2_b64 v[128:131], v222 offset1:4
	v_cvt_pk_f16_f32 v59, v34, v35
	v_cvt_pk_f16_f32 v58, v32, v33
	v_cvt_pk_f16_f32 v57, v22, v23
	v_mfma_f32_16x16x16_f16 v[48:51], v[0:1], v[48:49], 0
	v_cvt_pk_f16_f32 v56, v20, v21
	s_nop 2
	v_cvt_pk_f16_f32 v1, v38, v39
	v_cvt_pk_f16_f32 v0, v36, v37
	v_cvt_pk_f16_f32 v37, v46, v47
	v_cvt_pk_f16_f32 v36, v44, v45
	s_nop 0
	s_nop 0
	v_cvt_f16_f32_e32 v52, v52
	s_add_i32 s27, s26, 1
	v_mfma_f32_16x16x16_f16 v[44:47], v[0:1], v[36:37], v[44:47]
	v_cvt_pk_f16_f32 v37, v50, v51
	v_cvt_pk_f16_f32 v36, v48, v49
	s_nop 0
	s_nop 0
	v_mfma_f32_16x16x16_f16 v[36:39], v[36:37], v[0:1], 0
	s_nop 2
	v_cvt_pk_f16_f32 v1, v46, v47
	v_cvt_pk_f16_f32 v0, v44, v45
	s_nop 2
	v_cvt_pk_f16_f32 v49, v38, v39
	v_cvt_pk_f16_f32 v48, v36, v37
	s_nop 0
	s_nop 0
	s_waitcnt lgkmcnt(0)
	v_mfma_f32_16x16x32_f16 v[36:39], v[128:131], v[56:59], 0
	v_mfma_f32_16x16x16_f16 v[44:47], v[48:49], v[0:1], v[44:47]
	v_cvt_f16_f32_e32 v0, v60
	v_cvt_f16_f32_e32 v1, v61
	v_cvt_f16_f32_e32 v2, v62
	v_cvt_f16_f32_e32 v48, v63
	v_mfma_f32_16x16x32_f16 v[76:79], v[68:71], v[64:67], v[36:39]
	ds_read2_b64 v[72:75], v80 offset0:64 offset1:68
	ds_read2st64_b64 v[132:135], v223 offset0:20 offset1:25
	ds_read2_b64 v[68:71], v80 offset0:72 offset1:76
	s_nop 0
	s_nop 0
	v_cndmask_b32_e64 v0, 0, v0, s[10:11]
	v_cndmask_b32_e64 v49, 0, v1, s[14:15]
	v_cndmask_b32_e64 v1, 0, v2, s[16:17]
	v_cndmask_b32_e64 v2, 0, v48, s[20:21]
	v_pack_b32_f16 v1, v1, v2
	v_pack_b32_f16 v0, v0, v49
	s_nop 0
	s_nop 0
	s_waitcnt lgkmcnt(1)
	s_nop 0
	s_nop 0
	ds_read2_b64 v[128:131], v240 offset1:80
	s_nop 0
	s_nop 0
	v_cvt_f16_f32_e32 v36, v40
	ds_read_b128 v[136:139], v182
	v_cvt_f16_f32_e32 v40, v42
	v_mfma_f32_16x16x16_f16 v[48:51], v[0:1], v[132:133], v[76:79]
	v_cvt_pk_f16_f32 v1, v46, v47
	v_cvt_pk_f16_f32 v0, v44, v45
	v_cvt_f16_f32_e32 v37, v41
	s_nop 0
	s_nop 0
	s_nop 2
	v_cvt_pk_f16_f32 v77, v50, v51
	v_cvt_pk_f16_f32 v76, v48, v49
	v_cndmask_b32_e64 v88, v40, 0, s[18:19]
	v_mfma_f32_16x16x32_f16 v[56:59], v[72:75], v[56:59], 0
	v_cndmask_b32_e64 v36, v36, 0, s[12:13]
	v_cndmask_b32_e64 v37, 0, v37, s[10:11]
	s_nop 0
	v_mfma_f32_16x16x16_f16 v[44:47], v[0:1], v[76:77], 0
	ds_read_b64 v[76:77], v224 offset:5120
	ds_read_b128 v[140:143], v182 offset:64
	s_nop 0
	s_waitcnt lgkmcnt(4)
	v_mfma_f32_16x16x32_f16 v[56:59], v[68:71], v[64:67], v[56:59]
	s_nop 5
	v_cvt_pk_f16_f32 v1, v46, v47
	v_cvt_pk_f16_f32 v0, v44, v45
	s_nop 0
	s_nop 0
	s_nop 0
	s_nop 0
	s_waitcnt lgkmcnt(3)
	s_nop 0
	s_nop 0
	ds_read_b64 v[44:45], v225 offset:5120
	ds_read2_b64 v[144:147], v240 offset0:160 offset1:240
	s_nop 0
	s_waitcnt lgkmcnt(4)
	v_pk_mul_f32 v[50:51], v[22:23], v[138:139]
	v_pk_mul_f32 v[48:49], v[20:21], v[136:137]
	ds_read_b128 v[136:139], v182 offset:128
	s_nop 1
	v_mfma_f32_16x16x16_f16 v[48:51], v[128:129], v[0:1], v[48:51]
	v_cvt_f16_f32_e32 v80, v43
	v_cndmask_b32_e64 v89, v80, 0, s[22:23]
	s_nop 0
	s_waitcnt lgkmcnt(4)
	v_mfma_f32_16x16x16_f16 v[40:43], v[76:77], v[132:133], v[48:51]
	s_nop 3
	s_nop 0
	s_nop 0
	ds_read_b64 v[80:81], v226 offset:5120
	v_mov_b32_e32 v76, v130
	v_mov_b32_e32 v77, v131
	s_nop 0
	s_nop 0
	s_waitcnt lgkmcnt(4)
	v_pk_mul_f32 v[50:51], v[34:35], v[142:143]
	v_pk_mul_f32 v[48:49], v[32:33], v[140:141]
	s_nop 0
	ds_read_b128 v[128:131], v182 offset:192
	s_nop 0
	v_mfma_f32_16x16x16_f16 v[48:51], v[76:77], v[0:1], v[48:51]
	s_nop 0
	s_nop 0
	s_waitcnt lgkmcnt(3)
	s_nop 0
	v_mfma_f32_16x16x16_f16 v[48:51], v[44:45], v[132:133], v[48:51]
	s_nop 0
	s_nop 0
	s_nop 0
	v_pack_b32_f16 v77, v88, v89
	s_nop 0
	s_nop 0
	s_waitcnt lgkmcnt(2)
	v_pk_mul_f32 v[46:47], v[30:31], v[138:139]
	v_pk_mul_f32 v[44:45], v[28:29], v[136:137]
	s_nop 0
	v_pack_b32_f16 v76, v36, v37
	v_mfma_f32_16x16x16_f16 v[44:47], v[144:145], v[0:1], v[44:47]
	ds_read_b64 v[84:85], v227 offset:5120
	v_cndmask_b32_e64 v36, v52, 0, s[12:13]
	v_cvt_f16_f32_e32 v37, v53
	v_cndmask_b32_e64 v37, 0, v37, s[10:11]
	s_nop 0
	s_waitcnt lgkmcnt(2)
	v_mfma_f32_16x16x16_f16 v[44:47], v[80:81], v[132:133], v[44:47]
	s_nop 0
	s_nop 0
	v_pack_b32_f16 v72, v36, v37
	ds_read_b128 v[68:71], v228 offset:9216
	ds_read_b128 v[94:97], v228 offset:9280
	s_nop 0
	s_waitcnt lgkmcnt(3)
	v_pk_mul_f32 v[82:83], v[26:27], v[130:131]
	ds_read_b128 v[64:67], v228 offset:18432
	v_pk_mul_f32 v[80:81], v[24:25], v[128:129]
	s_nop 0
	ds_read_b128 v[98:101], v228 offset:23104
	v_mfma_f32_16x16x16_f16 v[78:81], v[146:147], v[0:1], v[80:83]
	ds_read_b128 v[90:93], v228 offset:18496
	s_nop 1
	v_cvt_f16_f32_e32 v82, v54
	v_cvt_f16_f32_e32 v83, v55
	s_nop 0
	s_waitcnt lgkmcnt(5)
	v_mfma_f32_16x16x16_f16 v[52:55], v[84:85], v[132:133], v[78:81]
	ds_read_b128 v[86:89], v228 offset:13824
	s_nop 1
	v_cndmask_b32_e64 v78, v82, 0, s[18:19]
	v_cndmask_b32_e64 v79, v83, 0, s[22:23]
	v_pack_b32_f16 v73, v78, v79
	s_nop 0
	s_nop 0
	v_add_u32_e32 v80, s77, v122
	v_add_u32_e32 v81, s76, v237
	v_mfma_f32_16x16x16_f16 v[56:59], v[76:77], v[0:1], v[56:59]
	ds_read_b128 v[76:79], v228 offset:23040
	v_subrev_u32_e32 v102, 64, v80
	v_add_u32_e32 v0, 0xff, v81
	v_mfma_f32_16x16x16_f16 v[58:61], v[72:73], v[132:133], v[56:59]
	v_cndmask_b32_e64 v0, v0, v102, s[2:3]
	v_add_u32_e32 v0, v0, v175
	s_not_b32 s30, s2
	s_xor_b32 s31, s88, s30
	s_sub_u32 s31, s31, s30
	v_mad_i64_i32 v[0:1], s[28:29], v0, s88, v[126:127]
	v_mov_b64_e32 v[248:249], v[0:1]
	s_nop 0
	s_waitcnt lgkmcnt(4)
	v_mfma_f32_16x16x32_f16 v[82:85], v[68:71], v[64:67], 0
	s_nop 2
	v_cvt_f16_f32_e32 v2, v58
	v_cvt_f16_f32_e32 v60, v60
	ds_read_b128 v[128:131], v228 offset:13888
	global_store_short v[0:1], v2, off
	s_nop 0
	s_nop 0
	v_cvt_f16_f32_e32 v2, v59
	s_nop 0
	v_mfma_f32_16x16x32_f16 v[72:75], v[64:67], v[68:71], 0
	s_nop 0
	s_nop 0
	s_mul_i32 s52, s31, 1
	s_mul_hi_i32 s53, s31, 1
	v_lshl_add_u64 v[0:1], v[248:249], 0, s[52:53]
	s_nop 0
	s_waitcnt lgkmcnt(2)
	v_mfma_f32_16x16x32_f16 v[62:65], v[64:67], v[86:89], 0
	global_store_short v[0:1], v2, off
	s_nop 0
	s_nop 0
	v_mfma_f32_16x16x32_f16 v[82:85], v[94:97], v[90:93], v[82:85]
	s_nop 0
	s_nop 0
	s_nop 0
	s_waitcnt lgkmcnt(1)
	v_mfma_f32_16x16x32_f16 v[68:71], v[76:79], v[68:71], 0
	v_mfma_f32_16x16x32_f16 v[86:89], v[76:79], v[86:89], 0
	s_nop 2
	v_cvt_f16_f32_e32 v1, v82
	v_cvt_f16_f32_e32 v2, v83
	v_cvt_f16_f32_e32 v66, v85
	v_mfma_f32_16x16x32_f16 v[72:75], v[90:93], v[94:97], v[72:75]
	s_nop 0
	v_cndmask_b32_e64 v66, 0, v66, s[22:23]
	s_nop 0
	s_waitcnt lgkmcnt(0)
	v_mfma_f32_16x16x32_f16 v[76:79], v[90:93], v[128:131], v[62:65]
	s_nop 0
	s_nop 2
	v_cndmask_b32_e64 v0, 0, v72, s[10:11]
	v_cndmask_b32_e64 v37, 0, v73, s[14:15]
	v_cvt_f16_f32_e32 v63, v84
	v_mfma_f32_16x16x32_f16 v[94:97], v[98:101], v[94:97], v[68:71]
	v_cndmask_b32_e64 v64, 0, v74, s[16:17]
	v_cndmask_b32_e64 v65, 0, v75, s[20:21]
	v_cndmask_b32_e64 v63, 0, v63, s[18:19]
	v_cndmask_b32_e64 v68, 0, v1, s[12:13]
	v_cndmask_b32_e64 v69, v2, 0, s[10:11]
	v_add_f32_e32 v62, v217, v0
	v_cvt_pk_f16_f32 v1, v64, v65
	v_cvt_pk_f16_f32 v0, v0, v37
	s_nop 0
	v_pack_b32_f16 v67, v63, v66
	v_pack_b32_f16 v66, v68, v69
	s_nop 0
	s_nop 0
	v_add_f32_e32 v63, v219, v37
	v_add_f32_e32 v64, v220, v64
	v_mfma_f32_16x16x16_f16 v[70:73], v[0:1], v[66:67], 0
	v_add_f32_e32 v65, v221, v65
	v_cvt_pk_f16_f32 v83, v64, v65
	v_cvt_pk_f16_f32 v82, v62, v63
	v_mfma_f32_16x16x16_f16 v[66:69], v[66:67], v[0:1], 0
	s_nop 0
	s_nop 2
	v_cvt_pk_f16_f32 v0, v70, v71
	s_nop 0
	s_nop 0
	v_cvt_pk_f16_f32 v1, v72, v73
	v_cvt_pk_f16_f32 v69, v68, v69
	v_cvt_pk_f16_f32 v68, v66, v67
	v_mfma_f32_16x16x16_f16 v[62:65], v[0:1], v[82:83], v[62:65]
	s_mul_i32 s52, s31, 2
	s_mul_hi_i32 s53, s31, 2
	v_lshl_add_u64 v[36:37], v[248:249], 0, s[52:53]
	global_store_short v[36:37], v60, off
	v_mfma_f32_16x16x16_f16 v[72:75], v[68:69], v[0:1], 0
	v_cvt_f16_f32_e32 v82, v61
	v_subrev_u32_e32 v36, 61, v80
	v_xad_u32 v37, v102, -4, v168
	v_mfma_f32_16x16x16_f16 v[66:69], v[0:1], v[68:69], 0
	s_nop 0
	v_cvt_pk_f16_f32 v71, v64, v65
	s_nop 1
	v_cvt_pk_f16_f32 v1, v74, v75
	v_cvt_pk_f16_f32 v0, v72, v73
	ds_read2_b64 v[136:139], v229 offset1:4
	v_mfma_f32_16x16x32_f16 v[56:59], v[98:101], v[128:131], v[86:89]
	v_cvt_pk_f16_f32 v70, v62, v63
	s_nop 0
	s_nop 0
	v_cvt_pk_f16_f32 v85, v68, v69
	ds_read2_b64 v[128:131], v229 offset0:8 offset1:12
	v_cvt_pk_f16_f32 v84, v66, v67
	s_nop 0
	s_nop 0
	v_mfma_f32_16x16x16_f16 v[88:91], v[0:1], v[70:71], v[62:65]
	s_nop 0
	s_nop 0
	v_cndmask_b32_e64 v36, v37, v36, s[2:3]
	v_mfma_f32_16x16x16_f16 v[60:63], v[84:85], v[0:1], 0
	v_add_u32_e32 v83, v36, v175
	s_nop 2
	v_cvt_pk_f16_f32 v1, v90, v91
	v_cvt_pk_f16_f32 v0, v88, v89
	v_cvt_pk_f16_f32 v67, v54, v55
	v_cvt_pk_f16_f32 v66, v52, v53
	v_cvt_pk_f16_f32 v85, v62, v63
	v_cvt_pk_f16_f32 v84, v60, v61
	v_cvt_pk_f16_f32 v63, v50, v51
	v_cvt_pk_f16_f32 v62, v48, v49
	v_cvt_pk_f16_f32 v61, v42, v43
	v_cvt_pk_f16_f32 v60, v40, v41
	v_cvt_pk_f16_f32 v65, v46, v47
	v_cvt_pk_f16_f32 v64, v44, v45
	s_nop 0
	s_waitcnt lgkmcnt(1)
	v_mfma_f32_16x16x32_f16 v[68:71], v[136:139], v[60:63], 0
	v_add_u32_e32 v36, 0x1000, v229
	s_nop 0
	v_cvt_f16_f32_e32 v76, v76
	s_nop 0
	s_waitcnt lgkmcnt(0)
	v_mfma_f32_16x16x32_f16 v[98:101], v[128:131], v[64:67], v[68:71]
	ds_read2_b64 v[72:75], v36 offset0:64 offset1:68
	s_nop 1
	ds_read2_b64 v[68:71], v36 offset0:72 offset1:76
	v_cvt_f16_f32_e32 v36, v97
	v_cvt_f16_f32_e32 v97, v77
	v_mfma_f32_16x16x16_f16 v[84:87], v[84:85], v[0:1], v[88:91]
	v_cvt_f16_f32_e32 v0, v94
	v_cvt_f16_f32_e32 v1, v95
	v_cvt_f16_f32_e32 v2, v96
	v_cndmask_b32_e64 v96, v76, 0, s[12:13]
	v_cndmask_b32_e64 v0, 0, v0, s[10:11]
	v_cndmask_b32_e64 v37, 0, v1, s[14:15]
	v_cndmask_b32_e64 v1, 0, v2, s[16:17]
	v_cndmask_b32_e64 v2, 0, v36, s[20:21]
	v_pack_b32_f16 v1, v1, v2
	v_pack_b32_f16 v0, v0, v37
	s_nop 0
	v_mov_b32_e32 v36, v134
	v_mov_b32_e32 v37, v135
	s_nop 0
	s_nop 0
	s_nop 0
	s_nop 0
	v_mfma_f32_16x16x16_f16 v[88:91], v[0:1], v[134:135], v[98:101]
	v_cvt_pk_f16_f32 v1, v86, v87
	v_cvt_pk_f16_f32 v0, v84, v85
	v_cvt_f16_f32_e32 v56, v56
	v_cvt_f16_f32_e32 v98, v78
	v_cvt_f16_f32_e32 v99, v79
	s_nop 2
	v_cvt_pk_f16_f32 v91, v90, v91
	v_cvt_pk_f16_f32 v90, v88, v89
	v_cndmask_b32_e64 v97, 0, v97, s[10:11]
	v_cndmask_b32_e64 v98, v98, 0, s[18:19]
	v_mfma_f32_16x16x16_f16 v[84:87], v[0:1], v[90:91], 0
	v_add_u32_e32 v2, 0x800, v240
	ds_read2_b64 v[128:131], v2 offset0:64 offset1:144
	ds_read_b128 v[76:79], v182 offset:256
	s_nop 0
	s_nop 0
	v_cndmask_b32_e64 v99, v99, 0, s[22:23]
	ds_read_b64 v[88:89], v230 offset:5120
	ds_read_b128 v[132:135], v182 offset:320
	s_nop 3
	v_cvt_pk_f16_f32 v1, v86, v87
	v_cvt_pk_f16_f32 v0, v84, v85
	s_nop 0
	s_nop 0
	s_nop 0
	s_nop 0
	s_nop 0
	s_waitcnt lgkmcnt(3)
	s_nop 0
	s_nop 0
	ds_read_b64 v[84:85], v231 offset:5120
	s_nop 0
	s_waitcnt lgkmcnt(3)
	v_pk_mul_f32 v[42:43], v[42:43], v[78:79]
	v_pk_mul_f32 v[40:41], v[40:41], v[76:77]
	s_nop 0
	s_nop 0
	v_mfma_f32_16x16x16_f16 v[40:43], v[128:129], v[0:1], v[40:43]
	s_nop 0
	s_waitcnt lgkmcnt(1)
	v_pk_mul_f32 v[48:49], v[48:49], v[132:133]
	v_add_u32_e32 v76, 0xc00, v240
	ds_read2_b64 v[136:139], v76 offset0:96 offset1:176
	ds_read_b128 v[140:143], v182 offset:384
	v_mfma_f32_16x16x16_f16 v[40:43], v[88:89], v[36:37], v[40:43]
	s_nop 0
	s_nop 0
	v_pk_mul_f32 v[50:51], v[50:51], v[134:135]
	s_nop 0
	s_nop 0
	s_nop 0
	v_mfma_f32_16x16x16_f16 v[48:51], v[130:131], v[0:1], v[48:51]
	ds_read_b64 v[88:89], v232 offset:5120
	s_nop 0
	s_waitcnt lgkmcnt(2)
	s_nop 0
	v_mfma_f32_16x16x16_f16 v[48:51], v[84:85], v[36:37], v[48:51]
	s_nop 0
	s_nop 0
	s_nop 0
	v_pack_b32_f16 v76, v96, v97
	v_cndmask_b32_e64 v96, v56, 0, s[12:13]
	s_nop 0
	s_waitcnt lgkmcnt(1)
	v_pk_mul_f32 v[46:47], v[46:47], v[142:143]
	v_pk_mul_f32 v[44:45], v[44:45], v[140:141]
	ds_read_b128 v[84:87], v182 offset:448
	v_cvt_f16_f32_e32 v56, v57
	v_cvt_f16_f32_e32 v57, v58
	v_mfma_f32_16x16x16_f16 v[44:47], v[136:137], v[0:1], v[44:47]
	v_cvt_f16_f32_e32 v58, v59
	s_nop 0
	s_nop 0
	s_nop 0
	s_waitcnt lgkmcnt(1)
	v_mfma_f32_16x16x16_f16 v[44:47], v[88:89], v[36:37], v[44:47]
	ds_read_b64 v[88:89], v233 offset:5120
	s_nop 0
	s_nop 0
	v_cndmask_b32_e64 v78, v57, 0, s[18:19]
	v_cndmask_b32_e64 v79, v58, 0, s[22:23]
	v_pack_b32_f16 v77, v98, v99
	s_nop 0
	s_waitcnt lgkmcnt(1)
	v_pk_mul_f32 v[52:53], v[52:53], v[84:85]
	v_cndmask_b32_e64 v84, 0, v56, s[10:11]
	v_mfma_f32_16x16x32_f16 v[56:59], v[72:75], v[60:63], 0
	v_pack_b32_f16 v61, v78, v79
	v_mov_b32_e32 v78, v3
	v_mov_b32_e32 v79, v3
	v_mfma_f32_16x16x32_f16 v[56:59], v[68:71], v[64:67], v[56:59]
	v_mul_f32_e64 v54, v54, v86
	v_mul_f32_e64 v55, v55, v87
	v_pack_b32_f16 v60, v96, v84
	s_nop 0
	s_nop 0
	v_mfma_f32_16x16x16_f16 v[52:55], v[138:139], v[0:1], v[52:55]
	v_mfma_f32_16x16x16_f16 v[56:59], v[76:77], v[0:1], v[56:59]
	s_mul_i32 s52, s31, 3
	s_mul_hi_i32 s53, s31, 3
	v_lshl_add_u64 v[0:1], v[248:249], 0, s[52:53]
	global_store_short v[0:1], v82, off
	s_nop 0
	s_waitcnt lgkmcnt(0)
	v_mfma_f32_16x16x16_f16 v[52:55], v[88:89], v[36:37], v[52:55]
	s_nop 0
	s_nop 0
	s_nop 0
	v_mfma_f32_16x16x16_f16 v[36:39], v[60:61], v[36:37], v[56:59]
	s_nop 0
	s_mul_i32 s52, s31, 16
	s_mul_hi_i32 s53, s31, 16
	v_lshl_add_u64 v[0:1], v[248:249], 0, s[52:53]
	s_nop 5
	v_cvt_f16_f32_e32 v2, v36
	global_store_short v[0:1], v2, off
	s_nop 0
	s_nop 0
	v_cvt_f16_f32_e32 v2, v37
	s_nop 0
	s_nop 0
	s_mul_i32 s52, s31, 17
	s_mul_hi_i32 s53, s31, 17
	v_lshl_add_u64 v[0:1], v[248:249], 0, s[52:53]
	global_store_short v[0:1], v2, off
	s_nop 0
	s_nop 0
	v_cvt_f16_f32_e32 v2, v38
	s_nop 0
	s_nop 0
	s_mul_i32 s52, s31, 18
	s_mul_hi_i32 s53, s31, 18
	v_lshl_add_u64 v[0:1], v[248:249], 0, s[52:53]
	global_store_short v[0:1], v2, off
	s_nop 0
	s_nop 0
	s_nop 0
	v_cvt_f16_f32_e32 v2, v39
	s_nop 0
	s_mul_i32 s52, s31, 19
	s_mul_hi_i32 s53, s31, 19
	v_lshl_add_u64 v[0:1], v[248:249], 0, s[52:53]
	s_mov_b64 s[28:29], 0
	global_store_short v[0:1], v2, off

.LBB0_1035:
	s_or_b64 exec, exec, s[26:27]
	s_waitcnt lgkmcnt(0)
	s_barrier
	ds_read_b128 v[40:43], v212 offset:9216
	ds_read_b128 v[48:51], v212 offset:18496
	ds_read_b128 v[56:59], v212 offset:9280
	ds_read_b128 v[60:63], v212 offset:23040
	ds_read_b128 v[36:39], v212 offset:18432
	s_nop 0
	s_nop 0
	s_nop 0
	ds_read_b128 v[64:67], v212 offset:13824
	s_waitcnt lgkmcnt(1)
	v_mfma_f32_16x16x32_f16 v[52:55], v[40:43], v[36:39], 0
	s_nop 0
	s_nop 0
	s_nop 0
	ds_read_b128 v[68:71], v212 offset:13888
	ds_read_b128 v[72:75], v212 offset:23104
	v_add_u32_e32 v80, 0x1000, v217
	s_nop 0
	v_mfma_f32_16x16x32_f16 v[52:55], v[56:59], v[48:51], v[52:55]
	s_nop 0
	s_nop 0
	s_nop 0
	v_mfma_f32_16x16x32_f16 v[44:47], v[36:39], v[40:43], 0
	s_nop 3
	v_cvt_f16_f32_e32 v0, v52
	v_cvt_f16_f32_e32 v1, v54
	v_cvt_f16_f32_e32 v2, v55
	v_mfma_f32_16x16x32_f16 v[44:47], v[48:51], v[56:59], v[44:47]
	v_cndmask_b32_e64 v79, 0, v0, s[12:13]
	v_cvt_f16_f32_e32 v0, v53
	v_cndmask_b32_e64 v54, 0, v1, s[18:19]
	s_nop 0
	v_mfma_f32_16x16x32_f16 v[40:43], v[60:63], v[40:43], 0
	v_cndmask_b32_e64 v55, 0, v2, s[22:23]
	s_nop 1
	v_cndmask_b32_e64 v76, 0, v44, s[10:11]
	v_cndmask_b32_e64 v77, 0, v45, s[14:15]
	s_nop 0
	s_waitcnt lgkmcnt(2)
	v_mfma_f32_16x16x32_f16 v[36:39], v[36:39], v[64:67], 0
	v_cndmask_b32_e64 v52, 0, v46, s[16:17]
	v_cndmask_b32_e64 v78, 0, v47, s[20:21]
	v_cndmask_b32_e64 v53, v0, 0, s[10:11]
	v_mfma_f32_16x16x32_f16 v[44:47], v[60:63], v[64:67], 0
	v_cvt_pk_f16_f32 v1, v52, v78
	v_cvt_pk_f16_f32 v0, v76, v77
	s_nop 0
	s_nop 0
	s_waitcnt lgkmcnt(0)
	v_mfma_f32_16x16x32_f16 v[60:63], v[72:75], v[56:59], v[40:43]
	v_add_f32_e32 v56, v213, v76
	v_add_f32_e32 v57, v214, v77
	v_add_f32_e32 v58, v215, v52
	v_mfma_f32_16x16x32_f16 v[40:43], v[48:51], v[68:71], v[36:39]
	v_add_f32_e32 v59, v216, v78
	v_cvt_pk_f16_f32 v67, v18, v19
	v_cvt_pk_f16_f32 v66, v16, v17
	v_pack_b32_f16 v37, v54, v55
	v_pack_b32_f16 v36, v79, v53
	s_nop 0
	s_nop 0
	v_mfma_f32_16x16x32_f16 v[52:55], v[72:75], v[68:71], v[44:47]
	ds_read2_b64 v[68:71], v217 offset0:8 offset1:12
	v_cvt_pk_f16_f32 v65, v14, v15
	v_cvt_pk_f16_f32 v64, v12, v13
	v_mfma_f32_16x16x16_f16 v[48:51], v[0:1], v[36:37], 0
	v_cvt_pk_f16_f32 v45, v58, v59
	v_cvt_pk_f16_f32 v44, v56, v57
	s_nop 0
	v_mfma_f32_16x16x16_f16 v[36:39], v[36:37], v[0:1], 0
	s_nop 0
	s_nop 2
	v_cvt_pk_f16_f32 v1, v50, v51
	v_cvt_pk_f16_f32 v0, v48, v49
	s_nop 0
	s_nop 0
	v_cvt_pk_f16_f32 v49, v38, v39
	v_cvt_pk_f16_f32 v48, v36, v37
	v_mfma_f32_16x16x16_f16 v[44:47], v[0:1], v[44:45], v[56:59]
	s_nop 0
	s_nop 0
	s_nop 0
	v_mfma_f32_16x16x16_f16 v[36:39], v[48:49], v[0:1], 0
	ds_read2_b64 v[126:129], v217 offset1:4
	v_cvt_pk_f16_f32 v59, v10, v11
	v_cvt_pk_f16_f32 v58, v8, v9
	v_cvt_pk_f16_f32 v57, v6, v7
	v_mfma_f32_16x16x16_f16 v[48:51], v[0:1], v[48:49], 0
	v_cvt_pk_f16_f32 v56, v4, v5
	s_nop 2
	v_cvt_pk_f16_f32 v1, v38, v39
	v_cvt_pk_f16_f32 v0, v36, v37
	v_cvt_pk_f16_f32 v37, v46, v47
	v_cvt_pk_f16_f32 v36, v44, v45
	s_nop 0
	s_nop 0
	v_cvt_f16_f32_e32 v52, v52
	s_add_i32 s28, s76, 1
	v_mfma_f32_16x16x16_f16 v[44:47], v[0:1], v[36:37], v[44:47]
	v_cvt_pk_f16_f32 v37, v50, v51
	v_cvt_pk_f16_f32 v36, v48, v49
	s_nop 0
	s_nop 0
	v_mfma_f32_16x16x16_f16 v[36:39], v[36:37], v[0:1], 0
	s_nop 2
	v_cvt_pk_f16_f32 v1, v46, v47
	v_cvt_pk_f16_f32 v0, v44, v45
	s_nop 2
	v_cvt_pk_f16_f32 v49, v38, v39
	v_cvt_pk_f16_f32 v48, v36, v37
	s_nop 0
	s_nop 0
	s_waitcnt lgkmcnt(0)
	v_mfma_f32_16x16x32_f16 v[36:39], v[126:129], v[56:59], 0
	v_mfma_f32_16x16x16_f16 v[44:47], v[48:49], v[0:1], v[44:47]
	v_cvt_f16_f32_e32 v0, v60
	v_cvt_f16_f32_e32 v1, v61
	v_cvt_f16_f32_e32 v2, v62
	v_cvt_f16_f32_e32 v48, v63
	v_mfma_f32_16x16x32_f16 v[76:79], v[68:71], v[64:67], v[36:39]
	ds_read2_b64 v[72:75], v80 offset0:64 offset1:68
	ds_read2st64_b64 v[130:133], v218 offset0:20 offset1:25
	ds_read2_b64 v[68:71], v80 offset0:72 offset1:76
	s_nop 0
	s_nop 0
	v_cndmask_b32_e64 v0, 0, v0, s[10:11]
	v_cndmask_b32_e64 v49, 0, v1, s[14:15]
	v_cndmask_b32_e64 v1, 0, v2, s[16:17]
	v_cndmask_b32_e64 v2, 0, v48, s[20:21]
	v_pack_b32_f16 v1, v1, v2
	v_pack_b32_f16 v0, v0, v49
	s_nop 0
	s_nop 0
	s_waitcnt lgkmcnt(1)
	s_nop 0
	s_nop 0
	ds_read2_b64 v[126:129], v233 offset1:80
	s_nop 0
	s_nop 0
	v_cvt_f16_f32_e32 v36, v40
	ds_read_b128 v[134:137], v178
	v_cvt_f16_f32_e32 v40, v42
	v_mfma_f32_16x16x16_f16 v[48:51], v[0:1], v[130:131], v[76:79]
	v_cvt_pk_f16_f32 v1, v46, v47
	v_cvt_pk_f16_f32 v0, v44, v45
	v_cvt_f16_f32_e32 v37, v41
	s_nop 0
	s_nop 0
	s_nop 2
	v_cvt_pk_f16_f32 v77, v50, v51
	v_cvt_pk_f16_f32 v76, v48, v49
	v_cndmask_b32_e64 v88, v40, 0, s[18:19]
	v_mfma_f32_16x16x32_f16 v[56:59], v[72:75], v[56:59], 0
	v_cndmask_b32_e64 v36, v36, 0, s[12:13]
	v_cndmask_b32_e64 v37, 0, v37, s[10:11]
	s_nop 0
	v_mfma_f32_16x16x16_f16 v[44:47], v[0:1], v[76:77], 0
	ds_read_b64 v[76:77], v219 offset:5120
	ds_read_b128 v[138:141], v178 offset:64
	s_nop 0
	s_waitcnt lgkmcnt(4)
	v_mfma_f32_16x16x32_f16 v[56:59], v[68:71], v[64:67], v[56:59]
	s_nop 5
	v_cvt_pk_f16_f32 v1, v46, v47
	v_cvt_pk_f16_f32 v0, v44, v45
	s_nop 0
	s_nop 0
	s_nop 0
	s_nop 0
	s_waitcnt lgkmcnt(3)
	s_nop 0
	s_nop 0
	ds_read_b64 v[44:45], v220 offset:5120
	ds_read2_b64 v[142:145], v233 offset0:160 offset1:240
	s_nop 0
	s_waitcnt lgkmcnt(4)
	v_pk_mul_f32 v[50:51], v[6:7], v[136:137]
	v_pk_mul_f32 v[48:49], v[4:5], v[134:135]
	ds_read_b128 v[134:137], v178 offset:128
	s_nop 1
	v_mfma_f32_16x16x16_f16 v[48:51], v[126:127], v[0:1], v[48:51]
	v_cvt_f16_f32_e32 v80, v43
	v_cndmask_b32_e64 v89, v80, 0, s[22:23]
	s_nop 0
	s_waitcnt lgkmcnt(4)
	v_mfma_f32_16x16x16_f16 v[40:43], v[76:77], v[130:131], v[48:51]
	s_nop 3
	s_nop 0
	s_nop 0
	ds_read_b64 v[80:81], v221 offset:5120
	v_mov_b32_e32 v76, v128
	v_mov_b32_e32 v77, v129
	s_nop 0
	s_nop 0
	s_waitcnt lgkmcnt(4)
	v_pk_mul_f32 v[50:51], v[10:11], v[140:141]
	v_pk_mul_f32 v[48:49], v[8:9], v[138:139]
	s_nop 0
	ds_read_b128 v[126:129], v178 offset:192
	s_nop 0
	v_mfma_f32_16x16x16_f16 v[48:51], v[76:77], v[0:1], v[48:51]
	s_nop 0
	s_nop 0
	s_waitcnt lgkmcnt(3)
	s_nop 0
	v_mfma_f32_16x16x16_f16 v[48:51], v[44:45], v[130:131], v[48:51]
	s_nop 0
	s_nop 0
	s_nop 0
	v_pack_b32_f16 v77, v88, v89
	s_nop 0
	s_nop 0
	s_waitcnt lgkmcnt(2)
	v_pk_mul_f32 v[46:47], v[14:15], v[136:137]
	v_pk_mul_f32 v[44:45], v[12:13], v[134:135]
	s_nop 0
	v_pack_b32_f16 v76, v36, v37
	v_mfma_f32_16x16x16_f16 v[44:47], v[142:143], v[0:1], v[44:47]
	ds_read_b64 v[84:85], v222 offset:5120
	v_cndmask_b32_e64 v36, v52, 0, s[12:13]
	v_cvt_f16_f32_e32 v37, v53
	v_cndmask_b32_e64 v37, 0, v37, s[10:11]
	s_nop 0
	s_waitcnt lgkmcnt(2)
	v_mfma_f32_16x16x16_f16 v[44:47], v[80:81], v[130:131], v[44:47]
	s_nop 0
	s_nop 0
	v_pack_b32_f16 v72, v36, v37
	ds_read_b128 v[68:71], v223 offset:9216
	ds_read_b128 v[94:97], v223 offset:9280
	s_nop 0
	s_waitcnt lgkmcnt(3)
	v_pk_mul_f32 v[82:83], v[18:19], v[128:129]
	ds_read_b128 v[64:67], v223 offset:18432
	v_pk_mul_f32 v[80:81], v[16:17], v[126:127]
	s_nop 0
	ds_read_b128 v[98:101], v223 offset:23104
	v_mfma_f32_16x16x16_f16 v[78:81], v[144:145], v[0:1], v[80:83]
	ds_read_b128 v[90:93], v223 offset:18496
	s_nop 1
	v_cvt_f16_f32_e32 v82, v54
	v_cvt_f16_f32_e32 v83, v55
	s_nop 0
	s_waitcnt lgkmcnt(5)
	v_mfma_f32_16x16x16_f16 v[52:55], v[84:85], v[130:131], v[78:81]
	ds_read_b128 v[86:89], v223 offset:13824
	s_nop 1
	v_cndmask_b32_e64 v78, v82, 0, s[18:19]
	v_cndmask_b32_e64 v79, v83, 0, s[22:23]
	v_pack_b32_f16 v73, v78, v79
	s_nop 0
	s_nop 0
	v_add_u32_e32 v80, s69, v153
	v_add_u32_e32 v81, s68, v232
	v_mfma_f32_16x16x16_f16 v[56:59], v[76:77], v[0:1], v[56:59]
	ds_read_b128 v[76:79], v223 offset:23040
	v_subrev_u32_e32 v102, 64, v80
	v_add_u32_e32 v0, 0x7ff, v81
	v_mfma_f32_16x16x16_f16 v[58:61], v[72:73], v[130:131], v[56:59]
	v_cndmask_b32_e64 v0, v0, v102, s[2:3]
	v_add_u32_e32 v0, v0, v151
	s_not_b32 s30, s2
	s_xor_b32 s31, s88, s30
	s_sub_u32 s31, s31, s30
	v_mad_i64_i32 v[0:1], s[26:27], v0, s88, v[122:123]
	v_mov_b64_e32 v[248:249], v[0:1]
	s_nop 0
	s_waitcnt lgkmcnt(4)
	v_mfma_f32_16x16x32_f16 v[82:85], v[68:71], v[64:67], 0
	s_nop 2
	v_cvt_f16_f32_e32 v2, v58
	v_cvt_f16_f32_e32 v60, v60
	ds_read_b128 v[126:129], v223 offset:13888
	global_store_short v[0:1], v2, off
	s_nop 0
	s_nop 0
	v_cvt_f16_f32_e32 v2, v59
	s_nop 0
	v_mfma_f32_16x16x32_f16 v[72:75], v[64:67], v[68:71], 0
	s_nop 0
	s_nop 0
	s_mul_i32 s52, s31, 1
	s_mul_hi_i32 s53, s31, 1
	v_lshl_add_u64 v[0:1], v[248:249], 0, s[52:53]
	s_nop 0
	s_waitcnt lgkmcnt(2)
	v_mfma_f32_16x16x32_f16 v[62:65], v[64:67], v[86:89], 0
	global_store_short v[0:1], v2, off
	s_nop 0
	s_nop 0
	v_mfma_f32_16x16x32_f16 v[82:85], v[94:97], v[90:93], v[82:85]
	s_nop 0
	s_nop 0
	s_nop 0
	s_waitcnt lgkmcnt(1)
	v_mfma_f32_16x16x32_f16 v[68:71], v[76:79], v[68:71], 0
	v_mfma_f32_16x16x32_f16 v[86:89], v[76:79], v[86:89], 0
	s_nop 2
	v_cvt_f16_f32_e32 v1, v82
	v_cvt_f16_f32_e32 v2, v83
	v_cvt_f16_f32_e32 v66, v85
	v_mfma_f32_16x16x32_f16 v[72:75], v[90:93], v[94:97], v[72:75]
	s_nop 0
	v_cndmask_b32_e64 v66, 0, v66, s[22:23]
	s_nop 0
	s_waitcnt lgkmcnt(0)
	v_mfma_f32_16x16x32_f16 v[76:79], v[90:93], v[126:129], v[62:65]
	s_nop 0
	s_nop 2
	v_cndmask_b32_e64 v0, 0, v72, s[10:11]
	v_cndmask_b32_e64 v37, 0, v73, s[14:15]
	v_cvt_f16_f32_e32 v63, v84
	v_mfma_f32_16x16x32_f16 v[94:97], v[98:101], v[94:97], v[68:71]
	v_cndmask_b32_e64 v64, 0, v74, s[16:17]
	v_cndmask_b32_e64 v65, 0, v75, s[20:21]
	v_cndmask_b32_e64 v63, 0, v63, s[18:19]
	v_cndmask_b32_e64 v68, 0, v1, s[12:13]
	v_cndmask_b32_e64 v69, v2, 0, s[10:11]
	v_add_f32_e32 v62, v213, v0
	v_cvt_pk_f16_f32 v1, v64, v65
	v_cvt_pk_f16_f32 v0, v0, v37
	s_nop 0
	v_pack_b32_f16 v67, v63, v66
	v_pack_b32_f16 v66, v68, v69
	s_nop 0
	s_nop 0
	v_add_f32_e32 v63, v214, v37
	v_add_f32_e32 v64, v215, v64
	v_mfma_f32_16x16x16_f16 v[70:73], v[0:1], v[66:67], 0
	v_add_f32_e32 v65, v216, v65
	v_cvt_pk_f16_f32 v83, v64, v65
	v_cvt_pk_f16_f32 v82, v62, v63
	v_mfma_f32_16x16x16_f16 v[66:69], v[66:67], v[0:1], 0
	s_nop 0
	s_nop 2
	v_cvt_pk_f16_f32 v0, v70, v71
	s_nop 0
	s_nop 0
	v_cvt_pk_f16_f32 v1, v72, v73
	v_cvt_pk_f16_f32 v69, v68, v69
	v_cvt_pk_f16_f32 v68, v66, v67
	v_mfma_f32_16x16x16_f16 v[62:65], v[0:1], v[82:83], v[62:65]
	s_mul_i32 s52, s31, 2
	s_mul_hi_i32 s53, s31, 2
	v_lshl_add_u64 v[36:37], v[248:249], 0, s[52:53]
	global_store_short v[36:37], v60, off
	v_mfma_f32_16x16x16_f16 v[72:75], v[68:69], v[0:1], 0
	v_cvt_f16_f32_e32 v82, v61
	v_subrev_u32_e32 v36, 61, v80
	v_xad_u32 v37, v102, -4, v172
	v_mfma_f32_16x16x16_f16 v[66:69], v[0:1], v[68:69], 0
	s_nop 0
	v_cvt_pk_f16_f32 v71, v64, v65
	s_nop 1
	v_cvt_pk_f16_f32 v1, v74, v75
	v_cvt_pk_f16_f32 v0, v72, v73
	ds_read2_b64 v[134:137], v224 offset1:4
	v_mfma_f32_16x16x32_f16 v[56:59], v[98:101], v[126:129], v[86:89]
	v_cvt_pk_f16_f32 v70, v62, v63
	s_nop 0
	s_nop 0
	v_cvt_pk_f16_f32 v85, v68, v69
	ds_read2_b64 v[126:129], v224 offset0:8 offset1:12
	v_cvt_pk_f16_f32 v84, v66, v67
	s_nop 0
	s_nop 0
	v_mfma_f32_16x16x16_f16 v[88:91], v[0:1], v[70:71], v[62:65]
	s_nop 0
	s_nop 0
	v_cndmask_b32_e64 v36, v37, v36, s[2:3]
	v_mfma_f32_16x16x16_f16 v[60:63], v[84:85], v[0:1], 0
	v_add_u32_e32 v83, v36, v151
	s_nop 2
	v_cvt_pk_f16_f32 v1, v90, v91
	v_cvt_pk_f16_f32 v0, v88, v89
	v_cvt_pk_f16_f32 v67, v54, v55
	v_cvt_pk_f16_f32 v66, v52, v53
	v_cvt_pk_f16_f32 v85, v62, v63
	v_cvt_pk_f16_f32 v84, v60, v61
	v_cvt_pk_f16_f32 v63, v50, v51
	v_cvt_pk_f16_f32 v62, v48, v49
	v_cvt_pk_f16_f32 v61, v42, v43
	v_cvt_pk_f16_f32 v60, v40, v41
	v_cvt_pk_f16_f32 v65, v46, v47
	v_cvt_pk_f16_f32 v64, v44, v45
	s_nop 0
	s_waitcnt lgkmcnt(1)
	v_mfma_f32_16x16x32_f16 v[68:71], v[134:137], v[60:63], 0
	v_add_u32_e32 v36, 0x1000, v224
	s_nop 0
	v_cvt_f16_f32_e32 v76, v76
	s_nop 0
	s_waitcnt lgkmcnt(0)
	v_mfma_f32_16x16x32_f16 v[98:101], v[126:129], v[64:67], v[68:71]
	ds_read2_b64 v[72:75], v36 offset0:64 offset1:68
	s_nop 1
	ds_read2_b64 v[68:71], v36 offset0:72 offset1:76
	v_cvt_f16_f32_e32 v36, v97
	v_cvt_f16_f32_e32 v97, v77
	v_mfma_f32_16x16x16_f16 v[84:87], v[84:85], v[0:1], v[88:91]
	v_cvt_f16_f32_e32 v0, v94
	v_cvt_f16_f32_e32 v1, v95
	v_cvt_f16_f32_e32 v2, v96
	v_cndmask_b32_e64 v96, v76, 0, s[12:13]
	v_cndmask_b32_e64 v0, 0, v0, s[10:11]
	v_cndmask_b32_e64 v37, 0, v1, s[14:15]
	v_cndmask_b32_e64 v1, 0, v2, s[16:17]
	v_cndmask_b32_e64 v2, 0, v36, s[20:21]
	v_pack_b32_f16 v1, v1, v2
	v_pack_b32_f16 v0, v0, v37
	s_nop 0
	v_mov_b32_e32 v36, v132
	v_mov_b32_e32 v37, v133
	s_nop 0
	s_nop 0
	s_nop 0
	s_nop 0
	v_mfma_f32_16x16x16_f16 v[88:91], v[0:1], v[132:133], v[98:101]
	v_cvt_pk_f16_f32 v1, v86, v87
	v_cvt_pk_f16_f32 v0, v84, v85
	v_cvt_f16_f32_e32 v56, v56
	v_cvt_f16_f32_e32 v98, v78
	v_cvt_f16_f32_e32 v99, v79
	s_nop 2
	v_cvt_pk_f16_f32 v91, v90, v91
	v_cvt_pk_f16_f32 v90, v88, v89
	v_cndmask_b32_e64 v97, 0, v97, s[10:11]
	v_cndmask_b32_e64 v98, v98, 0, s[18:19]
	v_mfma_f32_16x16x16_f16 v[84:87], v[0:1], v[90:91], 0
	v_add_u32_e32 v2, 0x800, v233
	ds_read2_b64 v[126:129], v2 offset0:64 offset1:144
	ds_read_b128 v[76:79], v178 offset:256
	s_nop 0
	s_nop 0
	v_cndmask_b32_e64 v99, v99, 0, s[22:23]
	ds_read_b64 v[88:89], v225 offset:5120
	ds_read_b128 v[130:133], v178 offset:320
	s_nop 3
	v_cvt_pk_f16_f32 v1, v86, v87
	v_cvt_pk_f16_f32 v0, v84, v85
	s_nop 0
	s_nop 0
	s_nop 0
	s_nop 0
	s_nop 0
	s_waitcnt lgkmcnt(3)
	s_nop 0
	s_nop 0
	ds_read_b64 v[84:85], v226 offset:5120
	s_nop 0
	s_waitcnt lgkmcnt(3)
	v_pk_mul_f32 v[42:43], v[42:43], v[78:79]
	v_pk_mul_f32 v[40:41], v[40:41], v[76:77]
	s_nop 0
	s_nop 0
	v_mfma_f32_16x16x16_f16 v[40:43], v[126:127], v[0:1], v[40:43]
	s_nop 0
	s_waitcnt lgkmcnt(1)
	v_pk_mul_f32 v[48:49], v[48:49], v[130:131]
	v_add_u32_e32 v76, 0xc00, v233
	ds_read2_b64 v[134:137], v76 offset0:96 offset1:176
	ds_read_b128 v[138:141], v178 offset:384
	v_mfma_f32_16x16x16_f16 v[40:43], v[88:89], v[36:37], v[40:43]
	s_nop 0
	s_nop 0
	v_pk_mul_f32 v[50:51], v[50:51], v[132:133]
	s_nop 0
	s_nop 0
	s_nop 0
	v_mfma_f32_16x16x16_f16 v[48:51], v[128:129], v[0:1], v[48:51]
	ds_read_b64 v[88:89], v227 offset:5120
	s_nop 0
	s_waitcnt lgkmcnt(2)
	s_nop 0
	v_mfma_f32_16x16x16_f16 v[48:51], v[84:85], v[36:37], v[48:51]
	s_nop 0
	s_nop 0
	s_nop 0
	v_pack_b32_f16 v76, v96, v97
	v_cndmask_b32_e64 v96, v56, 0, s[12:13]
	s_nop 0
	s_waitcnt lgkmcnt(1)
	v_pk_mul_f32 v[46:47], v[46:47], v[140:141]
	v_pk_mul_f32 v[44:45], v[44:45], v[138:139]
	ds_read_b128 v[84:87], v178 offset:448
	v_cvt_f16_f32_e32 v56, v57
	v_cvt_f16_f32_e32 v57, v58
	v_mfma_f32_16x16x16_f16 v[44:47], v[134:135], v[0:1], v[44:47]
	v_cvt_f16_f32_e32 v58, v59
	s_nop 0
	s_nop 0
	s_nop 0
	s_waitcnt lgkmcnt(1)
	v_mfma_f32_16x16x16_f16 v[44:47], v[88:89], v[36:37], v[44:47]
	ds_read_b64 v[88:89], v228 offset:5120
	s_nop 0
	s_nop 0
	v_cndmask_b32_e64 v78, v57, 0, s[18:19]
	v_cndmask_b32_e64 v79, v58, 0, s[22:23]
	v_pack_b32_f16 v77, v98, v99
	s_nop 0
	s_waitcnt lgkmcnt(1)
	v_pk_mul_f32 v[52:53], v[52:53], v[84:85]
	v_cndmask_b32_e64 v84, 0, v56, s[10:11]
	v_mfma_f32_16x16x32_f16 v[56:59], v[72:75], v[60:63], 0
	v_pack_b32_f16 v61, v78, v79
	v_mov_b32_e32 v78, v3
	v_mov_b32_e32 v79, v3
	v_mfma_f32_16x16x32_f16 v[56:59], v[68:71], v[64:67], v[56:59]
	v_mul_f32_e64 v54, v54, v86
	v_mul_f32_e64 v55, v55, v87
	v_pack_b32_f16 v60, v96, v84
	s_nop 0
	s_nop 0
	v_mfma_f32_16x16x16_f16 v[52:55], v[136:137], v[0:1], v[52:55]
	v_mfma_f32_16x16x16_f16 v[56:59], v[76:77], v[0:1], v[56:59]
	s_mul_i32 s52, s31, 3
	s_mul_hi_i32 s53, s31, 3
	v_lshl_add_u64 v[0:1], v[248:249], 0, s[52:53]
	global_store_short v[0:1], v82, off
	s_nop 0
	s_waitcnt lgkmcnt(0)
	v_mfma_f32_16x16x16_f16 v[52:55], v[88:89], v[36:37], v[52:55]
	s_nop 0
	s_nop 0
	s_nop 0
	v_mfma_f32_16x16x16_f16 v[36:39], v[60:61], v[36:37], v[56:59]
	s_nop 0
	s_mul_i32 s52, s31, 16
	s_mul_hi_i32 s53, s31, 16
	v_lshl_add_u64 v[0:1], v[248:249], 0, s[52:53]
	s_nop 5
	v_cvt_f16_f32_e32 v2, v36
	global_store_short v[0:1], v2, off
	s_nop 0
	s_nop 0
	v_cvt_f16_f32_e32 v2, v37
	s_nop 0
	s_nop 0
	s_mul_i32 s52, s31, 17
	s_mul_hi_i32 s53, s31, 17
	v_lshl_add_u64 v[0:1], v[248:249], 0, s[52:53]
	global_store_short v[0:1], v2, off
	s_nop 0
	s_nop 0
	v_cvt_f16_f32_e32 v2, v38
	s_nop 0
	s_nop 0
	s_mul_i32 s52, s31, 18
	s_mul_hi_i32 s53, s31, 18
	v_lshl_add_u64 v[0:1], v[248:249], 0, s[52:53]
	global_store_short v[0:1], v2, off
	s_nop 0
	s_nop 0
	s_nop 0
	v_cvt_f16_f32_e32 v2, v39
	s_nop 0
	s_mul_i32 s52, s31, 19
	s_mul_hi_i32 s53, s31, 19
	v_lshl_add_u64 v[0:1], v[248:249], 0, s[52:53]
	s_mov_b64 s[26:27], 0
	global_store_short v[0:1], v2, off
